# RESID epilogue: 8-lane sumsq butterfly via DPP quad_perm/row_half_mirror moves instead of 3 ds_bpermute round trips per pass
# speedup vs baseline: 1.0058x; 1.0058x over previous
; DI float fexp2(float x) { return __builtin_amdgcn_exp2f(x); }
; template <int EPI>
; DI void gemm_epilogue(const Ep& e, int m0, int n0) {
;     ...
; #pragma unroll
;     for (int p = 0; p < 8; ++p) {
;       const int row = p * 32 + (t >> 4), c8 = (t & 15) * 8;
;       const float4 a = *(const float4*)(T + row * 132 + c8), b = *(const float4*)(T + row * 132 + c8 + 4);
;       bf16_t* bp = e.xb + (size_t)(m0 + row) * DM + n0 + c8;
;       const uint4 xo4 = *(const uint4*)bp;
;     ...
;   if (t < 256) {
;     float rs = 1.f;
;     if (e.ss) {
;       const float* sp = e.ss + (size_t)(m0 + t) * e.nss;
;       float s = 0.f;
;       for (int i = 0; i < e.nss; ++i) s += sp[i];
;       rs = rsqrtf(s * e.inv_n + EPS);
;     }
;     ((float*)(smem + SMEM_RSTD))[t] = rs;
;   }
;   if constexpr (EPI == EPI_GU) {
;     __syncthreads();
;     const float* rstdL = (const float*)(smem + SMEM_RSTD);
; #pragma unroll
;     for (int ai = 0; ai < 2; ++ai)
; #pragma unroll
;       for (int m = 0; m < 4; ++m) {
;         const int rowb = ai * 128 + wr * 64 + m * 16 + fq * 4;
;         const f32x4 rs4 = *(const f32x4*)(rstdL + rowb);
; #pragma unroll
;         for (int bj = 0; bj < 2; ++bj) {
;           bf16_t* op = e.out + (size_t)(m0 + rowb) * e.ldo + ((n0 + bj * 128 + wc * 32) >> 1) + fr;
; #pragma unroll
;           for (int j = 0; j < 4; ++j) {
;             const float g = acc[ai][bj][m][0][j] * rs4[j], u = acc[ai][bj][m][1][j] * rs4[j];
;             const float rv = g * __builtin_amdgcn_rcpf(1.f + fexp2(-g * LOG2E)) * u;
;             op[(size_t)j * e.ldo] = (bf16_t)(pack2(rv, 0.f) & 0xffffu);
;           }
;         }
;       }
;     __syncthreads();
;     return;
;   }
;   float* T = (float*)smem;
; #pragma unroll
;   for (int bj = 0; bj < 2; ++bj) {
; #pragma unroll
;     for (int ai = 0; ai < 2; ++ai)
; #pragma unroll
;       for (int m = 0; m < 4; ++m)
; #pragma unroll
;         for (int n = 0; n < 2; ++n)
; #pragma unroll
;           for (int j = 0; j < 4; ++j)
;             T[(ai * 128 + wr * 64 + m * 16 + fq * 4 + j) * 132 + wc * 32 + n * 16 + fr] = acc[ai][bj][m][n][j];
;     __syncthreads();
.LBB0_911:
	s_or_b64 exec, exec, s[2:3]
	s_movk_i32 s2, 0x100
	v_cmp_gt_i32_e32 vcc, s2, v3
	s_waitcnt vmcnt(0)
	s_barrier
	s_and_saveexec_b64 s[2:3], vcc
	v_lshl_add_u32 v0, v3, 2, v234
	v_mov_b32_e32 v1, 1.0
	ds_write_b32 v0, v1
	s_or_b64 exec, exec, s[2:3]
	v_lshl_or_b32 v0, v148, 2, v149
	v_lshlrev_b32_e32 v1, 2, v147
	s_movk_i32 s12, 0x210
	v_lshl_or_b32 v1, v146, 7, v1
	v_mul_lo_u32 v0, v0, s12
	v_add_u32_e32 v132, v1, v0
	ds_write2_b32 v132, v104, v116 offset1:16
	ds_write2_b32 v132, v105, v117 offset0:132 offset1:148
	v_add_u32_e32 v104, 0x400, v132
	v_add_u32_e32 v105, 0x2000, v132
	ds_write2_b32 v104, v106, v118 offset0:8 offset1:24
	ds_write2_b32 v104, v107, v119 offset0:140 offset1:156
	ds_write2_b32 v105, v100, v108 offset0:64 offset1:80
	ds_write2_b32 v105, v101, v109 offset0:196 offset1:212
	v_add_u32_e32 v100, 0x2400, v132
	v_add_u32_e32 v101, 0x4000, v132
	ds_write2_b32 v100, v102, v110 offset0:72 offset1:88
	ds_write2_b32 v100, v103, v111 offset0:204 offset1:220
	ds_write2_b32 v101, v92, v96 offset0:128 offset1:144
	v_add_u32_e32 v92, 0x4400, v132
	ds_write2_b32 v92, v93, v97 offset0:4 offset1:20
	ds_write2_b32 v92, v94, v98 offset0:136 offset1:152
	v_add_u32_e32 v94, 0x6000, v132
	v_add_u32_e32 v93, 0x4800, v132
	ds_write2_b32 v94, v84, v88 offset0:192 offset1:208
	v_add_u32_e32 v84, 0x6400, v132
	v_or_b32_e32 v3, 64, v1
	ds_write2_b32 v93, v95, v99 offset0:12 offset1:28
	ds_write2_b32 v84, v85, v89 offset0:68 offset1:84
	ds_write2_b32 v84, v86, v90 offset0:200 offset1:216
	v_add_u32_e32 v85, 0x6800, v132
	v_add_u32_e32 v90, 0x10800, v0
	ds_write2_b32 v85, v87, v91 offset0:76 offset1:92
	v_add_u32_e32 v86, v1, v90
	v_add_u32_e32 v91, 0x10a10, v0
	v_add_u32_e32 v90, v3, v90
	v_add_u32_e32 v95, 0x10c20, v0
	ds_write_b32 v90, v124
	v_add_u32_e32 v90, v3, v91
	v_add_u32_e32 v96, 0x10e30, v0
	ds_write_b32 v90, v125
	v_add_u32_e32 v90, v3, v95
	ds_write_b32 v90, v126
	v_add_u32_e32 v90, v3, v96
	v_add_u32_e32 v97, 0x12900, v0
	ds_write_b32 v90, v127
	v_add_u32_e32 v90, v1, v97
	v_add_u32_e32 v98, 0x12b10, v0
	v_add_u32_e32 v97, v3, v97
	v_add_u32_e32 v99, 0x12d20, v0
	ds_write_b32 v97, v112
	v_add_u32_e32 v97, v3, v98
	v_add_u32_e32 v102, 0x12f30, v0
	ds_write_b32 v97, v113
	v_add_u32_e32 v97, v3, v99
	v_add_u32_e32 v87, v1, v91
	v_add_u32_e32 v91, v1, v98
	ds_write_b32 v97, v114
	v_add_u32_e32 v97, v3, v102
	v_add_u32_e32 v98, 0x14a00, v0
	v_add_u32_e32 v88, v1, v95
	v_add_u32_e32 v95, v1, v99
	ds_write_b32 v97, v115
	v_add_u32_e32 v97, v1, v98
	v_add_u32_e32 v99, 0x14c10, v0
	v_add_u32_e32 v89, v1, v96
	v_add_u32_e32 v96, v1, v102
	ds_write_b32 v97, v80
	v_add_u32_e32 v80, v1, v99
	v_add_u32_e32 v102, 0x14e20, v0
	ds_write_b32 v80, v81
	v_add_u32_e32 v81, v1, v102
	v_add_u32_e32 v103, 0x15030, v0
	ds_write_b32 v81, v82
	v_add_u32_e32 v82, v1, v103
	ds_write_b32 v82, v83
	v_add_u32_e32 v83, v3, v98
	ds_write_b32 v83, v76
	v_add_u32_e32 v76, v3, v99
	ds_write_b32 v76, v77
	v_add_u32_e32 v76, v3, v102
	ds_write_b32 v76, v78
	v_add_u32_e32 v76, v3, v103
	v_add_u32_e32 v83, 0x16b00, v0
	ds_write_b32 v76, v79
	v_add_u32_e32 v76, v1, v83
	ds_write_b32 v76, v72
	v_add_u32_e32 v72, 0x16d10, v0
	v_add_u32_e32 v77, v1, v72
	ds_write_b32 v77, v73
	v_add_u32_e32 v73, 0x16f20, v0
	v_add_u32_e32 v0, 0x17130, v0
	v_add_u32_e32 v78, v1, v73
	v_add_u32_e32 v79, v1, v0
	v_add_u32_e32 v1, v3, v83
	ds_write_b32 v1, v68
	v_add_u32_e32 v1, v3, v72
	ds_write_b32 v1, v69
	v_add_u32_e32 v1, v3, v73
	v_add_u32_e32 v0, v3, v0
	v_mov_b32_e32 v73, v224
	ds_write_b32 v86, v128
	ds_write_b32 v87, v129
	ds_write_b32 v88, v130
	ds_write_b32 v89, v131
	ds_write_b32 v90, v120
	ds_write_b32 v91, v121
	ds_write_b32 v95, v122
	ds_write_b32 v96, v123
	ds_write_b32 v78, v74
	ds_write_b32 v79, v75
	ds_write_b32 v1, v70
	ds_write_b32 v0, v71
	s_waitcnt lgkmcnt(0)
	s_barrier
	v_mov_b32_e32 v71, v2
	v_ashrrev_i32_e32 v72, 4, v73
	v_add_u32_e32 v68, s25, v72
	v_lshlrev_b32_e32 v0, 3, v73
	v_ashrrev_i32_e32 v69, 31, v68
	v_and_b32_e32 v99, 0x78, v0
	v_lshlrev_b64 v[0:1], 11, v[68:69]
	v_lshl_add_u64 v[0:1], s[6:7], 0, v[0:1]
	v_lshl_add_u64 v[0:1], s[8:9], 1, v[0:1]
	v_lshlrev_b32_e32 v70, 1, v99
	v_lshl_add_u64 v[102:103], v[0:1], 0, v[70:71]
	v_mov_b32_e32 v226, 0x10000
	v_mov_b32_e32 v227, 0
	global_load_dwordx4 v[156:159], v[102:103], off
	v_lshl_add_u64 v[236:237], v[102:103], 0, v[226:227]
	global_load_dwordx4 v[160:163], v[236:237], off
	v_lshl_add_u64 v[238:239], v[236:237], 0, v[226:227]
	global_load_dwordx4 v[164:167], v[238:239], off
	v_lshl_add_u64 v[240:241], v[238:239], 0, v[226:227]
	global_load_dwordx4 v[168:171], v[240:241], off
	v_lshl_add_u64 v[242:243], v[240:241], 0, v[226:227]
	global_load_dwordx4 v[172:175], v[242:243], off
	v_lshl_add_u64 v[244:245], v[242:243], 0, v[226:227]
	global_load_dwordx4 v[176:179], v[244:245], off
	v_lshl_add_u64 v[246:247], v[244:245], 0, v[226:227]
	global_load_dwordx4 v[180:183], v[246:247], off
	v_lshl_add_u64 v[248:249], v[246:247], 0, v[226:227]
	global_load_dwordx4 v[184:187], v[248:249], off
	global_load_dwordx4 v[188:191], v[102:103], off offset:256
	global_load_dwordx4 v[192:195], v[236:237], off offset:256
	global_load_dwordx4 v[196:199], v[238:239], off offset:256
	global_load_dwordx4 v[200:203], v[240:241], off offset:256
	global_load_dwordx4 v[204:207], v[242:243], off offset:256
	global_load_dwordx4 v[208:211], v[244:245], off offset:256
	global_load_dwordx4 v[212:215], v[246:247], off offset:256
	global_load_dwordx4 v[216:219], v[248:249], off offset:256
	v_and_b32_e32 v1, 64, v225
	v_lshlrev_b32_e32 v83, 2, v99
	v_xor_b32_e32 v0, 1, v225
	v_add_u32_e32 v98, 64, v1
	v_mul_lo_u32 v72, v72, s12
	v_cmp_lt_i32_e32 vcc, v0, v98
	v_add_u32_e32 v114, v83, v72
	ds_read_b128 v[110:113], v114
	v_cndmask_b32_e32 v0, v225, v0, vcc
	v_lshlrev_b32_e32 v3, 2, v0
	ds_read_b128 v[114:117], v114 offset:16
	v_xor_b32_e32 v118, 2, v225
	v_cmp_lt_i32_e32 vcc, v118, v98
	v_and_b32_e32 v73, 7, v73
	s_add_u32 s2, s0, 0xf640000
	s_addc_u32 s3, s1, 0
	s_waitcnt vmcnt(15)
; DI float h_lo(unsigned u) { return (float)__builtin_bit_cast(h2_t, u)[0]; }
; DI float h_hi(unsigned u) { return (float)__builtin_bit_cast(h2_t, u)[1]; }
; template <int EPI>
; DI void gemm_epilogue(const Ep& e, int m0, int n0) {
;     ...
; #pragma unroll
;     for (int p = 0; p < 8; ++p) {
;       const int row = p * 32 + (t >> 4), c8 = (t & 15) * 8;
;       const float4 a = *(const float4*)(T + row * 132 + c8), b = *(const float4*)(T + row * 132 + c8 + 4);
;       bf16_t* bp = e.xb + (size_t)(m0 + row) * DM + n0 + c8;
;       const uint4 xo4 = *(const uint4*)bp;
;       uint4 u;
;       u.x = pack2h(h_lo(xo4.x) + a.x, h_hi(xo4.x) + a.y); u.y = pack2h(h_lo(xo4.y) + a.z, h_hi(xo4.y) + a.w);
;       u.z = pack2h(h_lo(xo4.z) + b.x, h_hi(xo4.z) + b.y); u.w = pack2h(h_lo(xo4.w) + b.z, h_hi(xo4.w) + b.w);
;       *(uint4*)bp = u;
;       const float r0 = h_lo(u.x), r1 = h_hi(u.x), r2 = h_lo(u.y), r3 = h_hi(u.y);
;       const float r4 = h_lo(u.z), r5 = h_hi(u.z), r6 = h_lo(u.w), r7 = h_hi(u.w);
;       float s2 = r0 * r0 + r1 * r1 + r2 * r2 + r3 * r3 + r4 * r4 + r5 * r5 + r6 * r6 + r7 * r7;
;       s2 += __shfl_xor(s2, 1); s2 += __shfl_xor(s2, 2); s2 += __shfl_xor(s2, 4);
;       if ((t & 7) == 0) e.ss_out[(size_t)(m0 + row) * 16 + ((n0 + c8) >> 6)] = s2;
	v_mov_b32_e32 v106, v156
	v_mov_b32_e32 v107, v157
	v_mov_b32_e32 v108, v158
	v_mov_b32_e32 v109, v159
	v_cvt_f32_f16_e32 v0, v106
	v_cvt_f32_f16_sdwa v1, v106 dst_sel:DWORD dst_unused:UNUSED_PAD src0_sel:WORD_1
	v_cvt_f32_f16_e32 v74, v107
	v_cvt_f32_f16_sdwa v75, v107 dst_sel:DWORD dst_unused:UNUSED_PAD src0_sel:WORD_1
	s_waitcnt lgkmcnt(1)
	v_pk_add_f32 v[0:1], v[110:111], v[0:1]
	s_nop 0
	v_cvt_pk_f16_f32 v106, v0, v1
	v_pk_add_f32 v[0:1], v[112:113], v[74:75]
	v_cvt_f32_f16_sdwa v110, v106 dst_sel:DWORD dst_unused:UNUSED_PAD src0_sel:WORD_1
	v_cvt_pk_f16_f32 v107, v0, v1
	v_cvt_f32_f16_e32 v0, v109
	v_cvt_f32_f16_sdwa v1, v109 dst_sel:DWORD dst_unused:UNUSED_PAD src0_sel:WORD_1
	v_cvt_f32_f16_e32 v74, v108
	v_cvt_f32_f16_sdwa v75, v108 dst_sel:DWORD dst_unused:UNUSED_PAD src0_sel:WORD_1
	s_waitcnt lgkmcnt(0)
	v_pk_add_f32 v[0:1], v[116:117], v[0:1]
	s_nop 0
	v_cvt_pk_f16_f32 v109, v0, v1
	v_mul_f32_e32 v0, v110, v110
	v_fma_mix_f32 v0, v106, v106, v0 op_sel_hi:[1,1,0]
	v_pk_add_f32 v[74:75], v[114:115], v[74:75]
	v_fma_mix_f32 v0, v107, v107, v0 op_sel_hi:[1,1,0]
	v_cvt_pk_f16_f32 v108, v74, v75
	v_fma_mix_f32 v0, v107, v107, v0 op_sel:[1,1,0] op_sel_hi:[1,1,0]
	v_cndmask_b32_e32 v74, v225, v118, vcc
	v_fma_mix_f32 v0, v108, v108, v0 op_sel_hi:[1,1,0]
	v_lshlrev_b32_e32 v74, 2, v74
	v_fma_mix_f32 v0, v108, v108, v0 op_sel:[1,1,0] op_sel_hi:[1,1,0]
	v_xor_b32_e32 v75, 4, v225
	v_fma_mix_f32 v0, v109, v109, v0 op_sel_hi:[1,1,0]
	v_cmp_lt_i32_e32 vcc, v75, v98
	v_fma_mix_f32 v0, v109, v109, v0 op_sel:[1,1,0] op_sel_hi:[1,1,0]
	s_nop 1
	v_mov_b32_dpp v1, v0 quad_perm:[1,0,3,2] row_mask:0xf bank_mask:0xf
	v_cndmask_b32_e32 v75, v225, v75, vcc
	v_lshlrev_b32_e32 v75, 2, v75
	v_cmp_eq_u32_e32 vcc, 0, v73
	global_store_dwordx4 v[102:103], v[106:109], off
	s_waitcnt lgkmcnt(0)
	v_add_f32_e32 v0, v0, v1
	s_nop 1
	v_mov_b32_dpp v1, v0 quad_perm:[2,3,0,1] row_mask:0xf bank_mask:0xf
	s_waitcnt lgkmcnt(0)
	v_add_f32_e32 v73, v0, v1
	s_nop 1
	v_mov_b32_dpp v98, v73 row_half_mirror row_mask:0xf bank_mask:0xf
	v_or_b32_e32 v0, s8, v99
	v_ashrrev_i32_e32 v0, 6, v0
	v_ashrrev_i32_e32 v1, 31, v0
	s_and_saveexec_b64 s[0:1], vcc
	s_cbranch_execz .LBB0_915
	v_lshlrev_b64 v[102:103], 6, v[68:69]
	v_lshl_add_u64 v[102:103], s[2:3], 0, v[102:103]
	v_lshl_add_u64 v[102:103], v[0:1], 2, v[102:103]
	s_waitcnt lgkmcnt(0)
	v_add_f32_e32 v69, v73, v98
	global_store_dword v[102:103], v69, off
.LBB0_915:
	s_or_b64 exec, exec, s[0:1]
	v_add_u32_e32 v69, 0x4200, v72
	v_add_u32_e32 v72, 32, v68
	v_ashrrev_i32_e32 v73, 31, v72
	s_waitcnt lgkmcnt(0)
	v_lshlrev_b64 v[98:99], 11, v[72:73]
	v_lshl_add_u64 v[98:99], s[6:7], 0, v[98:99]
	v_lshl_add_u64 v[98:99], s[8:9], 1, v[98:99]
	v_lshl_add_u64 v[98:99], v[98:99], 0, v[70:71]
	v_add_u32_e32 v102, v83, v69
	ds_read_b128 v[110:113], v102
	ds_read_b128 v[114:117], v102 offset:16
	s_waitcnt vmcnt(15)
	v_mov_b32_e32 v106, v160
	v_mov_b32_e32 v107, v161
	v_mov_b32_e32 v108, v162
	v_mov_b32_e32 v109, v163
	v_cvt_f32_f16_e32 v102, v106
	v_cvt_f32_f16_sdwa v103, v106 dst_sel:DWORD dst_unused:UNUSED_PAD src0_sel:WORD_1
	s_waitcnt lgkmcnt(1)
	v_pk_add_f32 v[102:103], v[110:111], v[102:103]
	s_nop 0
	v_cvt_pk_f16_f32 v106, v102, v103
	v_cvt_f32_f16_e32 v102, v107
	v_cvt_f32_f16_sdwa v103, v107 dst_sel:DWORD dst_unused:UNUSED_PAD src0_sel:WORD_1
	v_cvt_f32_f16_sdwa v71, v106 dst_sel:DWORD dst_unused:UNUSED_PAD src0_sel:WORD_1
	v_pk_add_f32 v[102:103], v[112:113], v[102:103]
	s_nop 0
	v_cvt_pk_f16_f32 v107, v102, v103
	v_cvt_f32_f16_e32 v102, v108
	v_cvt_f32_f16_sdwa v103, v108 dst_sel:DWORD dst_unused:UNUSED_PAD src0_sel:WORD_1
	v_mul_f32_e32 v71, v71, v71
	v_fma_mix_f32 v71, v106, v106, v71 op_sel_hi:[1,1,0]
	s_waitcnt lgkmcnt(0)
	v_pk_add_f32 v[102:103], v[114:115], v[102:103]
	s_nop 0
	v_cvt_pk_f16_f32 v108, v102, v103
	v_cvt_f32_f16_e32 v102, v109
	v_cvt_f32_f16_sdwa v103, v109 dst_sel:DWORD dst_unused:UNUSED_PAD src0_sel:WORD_1
	v_fma_mix_f32 v71, v107, v107, v71 op_sel_hi:[1,1,0]
	v_pk_add_f32 v[102:103], v[116:117], v[102:103]
	v_fma_mix_f32 v71, v107, v107, v71 op_sel:[1,1,0] op_sel_hi:[1,1,0]
	v_cvt_pk_f16_f32 v109, v102, v103
	v_fma_mix_f32 v71, v108, v108, v71 op_sel_hi:[1,1,0]
	global_store_dwordx4 v[98:99], v[106:109], off
	v_fma_mix_f32 v71, v108, v108, v71 op_sel:[1,1,0] op_sel_hi:[1,1,0]
	s_nop 0
	v_fma_mix_f32 v71, v109, v109, v71 op_sel_hi:[1,1,0]
	s_nop 0
	v_fma_mix_f32 v71, v109, v109, v71 op_sel:[1,1,0] op_sel_hi:[1,1,0]
	s_nop 1
	v_mov_b32_dpp v98, v71 quad_perm:[1,0,3,2] row_mask:0xf bank_mask:0xf
	s_waitcnt lgkmcnt(0)
	v_add_f32_e32 v71, v71, v98
	s_nop 1
	v_mov_b32_dpp v98, v71 quad_perm:[2,3,0,1] row_mask:0xf bank_mask:0xf
	s_waitcnt lgkmcnt(0)
	v_add_f32_e32 v71, v71, v98
	s_nop 1
	v_mov_b32_dpp v98, v71 row_half_mirror row_mask:0xf bank_mask:0xf
	s_and_saveexec_b64 s[0:1], vcc
	s_cbranch_execz .LBB0_917
	v_lshlrev_b64 v[72:73], 6, v[72:73]
	v_lshl_add_u64 v[72:73], s[2:3], 0, v[72:73]
	v_lshl_add_u64 v[72:73], v[0:1], 2, v[72:73]
	s_waitcnt lgkmcnt(0)
	v_add_f32_e32 v71, v71, v98
	global_store_dword v[72:73], v71, off
; DI float h_lo(unsigned u) { return (float)__builtin_bit_cast(h2_t, u)[0]; }
; DI float h_hi(unsigned u) { return (float)__builtin_bit_cast(h2_t, u)[1]; }
; template <int EPI>
; DI void gemm_epilogue(const Ep& e, int m0, int n0) {
;     ...
; #pragma unroll
;     for (int p = 0; p < 8; ++p) {
;       const int row = p * 32 + (t >> 4), c8 = (t & 15) * 8;
;       const float4 a = *(const float4*)(T + row * 132 + c8), b = *(const float4*)(T + row * 132 + c8 + 4);
;       bf16_t* bp = e.xb + (size_t)(m0 + row) * DM + n0 + c8;
;       const uint4 xo4 = *(const uint4*)bp;
;       uint4 u;
;       u.x = pack2h(h_lo(xo4.x) + a.x, h_hi(xo4.x) + a.y); u.y = pack2h(h_lo(xo4.y) + a.z, h_hi(xo4.y) + a.w);
;       u.z = pack2h(h_lo(xo4.z) + b.x, h_hi(xo4.z) + b.y); u.w = pack2h(h_lo(xo4.w) + b.z, h_hi(xo4.w) + b.w);
;       *(uint4*)bp = u;
;       const float r0 = h_lo(u.x), r1 = h_hi(u.x), r2 = h_lo(u.y), r3 = h_hi(u.y);
;       const float r4 = h_lo(u.z), r5 = h_hi(u.z), r6 = h_lo(u.w), r7 = h_hi(u.w);
;       float s2 = r0 * r0 + r1 * r1 + r2 * r2 + r3 * r3 + r4 * r4 + r5 * r5 + r6 * r6 + r7 * r7;
;       s2 += __shfl_xor(s2, 1); s2 += __shfl_xor(s2, 2); s2 += __shfl_xor(s2, 4);
;       if ((t & 7) == 0) e.ss_out[(size_t)(m0 + row) * 16 + ((n0 + c8) >> 6)] = s2;
.LBB0_917:
	s_or_b64 exec, exec, s[0:1]
	v_add_u32_e32 v72, 64, v68
	v_ashrrev_i32_e32 v73, 31, v72
	s_waitcnt lgkmcnt(0)
	v_lshlrev_b64 v[98:99], 11, v[72:73]
	v_lshl_add_u64 v[98:99], s[6:7], 0, v[98:99]
	v_lshl_add_u64 v[98:99], s[8:9], 1, v[98:99]
	v_mov_b32_e32 v71, v2
	v_lshl_add_u64 v[98:99], v[98:99], 0, v[70:71]
	v_add_u32_e32 v69, 0x4200, v69
	v_add_u32_e32 v102, v83, v69
	ds_read_b128 v[110:113], v102
	ds_read_b128 v[114:117], v102 offset:16
	s_waitcnt vmcnt(15)
	v_mov_b32_e32 v106, v164
	v_mov_b32_e32 v107, v165
	v_mov_b32_e32 v108, v166
	v_mov_b32_e32 v109, v167
	v_cvt_f32_f16_e32 v102, v106
	v_cvt_f32_f16_sdwa v103, v106 dst_sel:DWORD dst_unused:UNUSED_PAD src0_sel:WORD_1
	s_waitcnt lgkmcnt(1)
	v_pk_add_f32 v[102:103], v[110:111], v[102:103]
	s_nop 0
	v_cvt_pk_f16_f32 v106, v102, v103
	v_cvt_f32_f16_e32 v102, v107
	v_cvt_f32_f16_sdwa v103, v107 dst_sel:DWORD dst_unused:UNUSED_PAD src0_sel:WORD_1
	v_pk_add_f32 v[102:103], v[112:113], v[102:103]
	s_nop 0
	v_cvt_pk_f16_f32 v107, v102, v103
	v_cvt_f32_f16_e32 v102, v108
	v_cvt_f32_f16_sdwa v103, v108 dst_sel:DWORD dst_unused:UNUSED_PAD src0_sel:WORD_1
	s_waitcnt lgkmcnt(0)
	v_pk_add_f32 v[102:103], v[114:115], v[102:103]
	s_nop 0
	v_cvt_pk_f16_f32 v108, v102, v103
	v_cvt_f32_f16_e32 v102, v109
	v_cvt_f32_f16_sdwa v103, v109 dst_sel:DWORD dst_unused:UNUSED_PAD src0_sel:WORD_1
	v_pk_add_f32 v[102:103], v[116:117], v[102:103]
	s_nop 0
	v_cvt_pk_f16_f32 v109, v102, v103
	global_store_dwordx4 v[98:99], v[106:109], off
	v_cvt_f32_f16_sdwa v98, v106 dst_sel:DWORD dst_unused:UNUSED_PAD src0_sel:WORD_1
	v_mul_f32_e32 v98, v98, v98
	v_fma_mix_f32 v98, v106, v106, v98 op_sel_hi:[1,1,0]
	s_nop 0
	v_fma_mix_f32 v98, v107, v107, v98 op_sel_hi:[1,1,0]
	s_nop 0
	v_fma_mix_f32 v98, v107, v107, v98 op_sel:[1,1,0] op_sel_hi:[1,1,0]
	s_nop 0
	v_fma_mix_f32 v98, v108, v108, v98 op_sel_hi:[1,1,0]
	s_nop 0
	v_fma_mix_f32 v98, v108, v108, v98 op_sel:[1,1,0] op_sel_hi:[1,1,0]
	s_nop 0
	v_fma_mix_f32 v98, v109, v109, v98 op_sel_hi:[1,1,0]
	s_nop 0
	v_fma_mix_f32 v98, v109, v109, v98 op_sel:[1,1,0] op_sel_hi:[1,1,0]
	s_nop 1
	v_mov_b32_dpp v99, v98 quad_perm:[1,0,3,2] row_mask:0xf bank_mask:0xf
	s_waitcnt lgkmcnt(0)
	v_add_f32_e32 v98, v98, v99
	s_nop 1
	v_mov_b32_dpp v99, v98 quad_perm:[2,3,0,1] row_mask:0xf bank_mask:0xf
	s_waitcnt lgkmcnt(0)
	v_add_f32_e32 v98, v98, v99
	s_nop 1
	v_mov_b32_dpp v99, v98 row_half_mirror row_mask:0xf bank_mask:0xf
	s_and_saveexec_b64 s[0:1], vcc
	s_cbranch_execz .LBB0_919
	v_lshlrev_b64 v[72:73], 6, v[72:73]
	v_lshl_add_u64 v[72:73], s[2:3], 0, v[72:73]
	v_lshl_add_u64 v[72:73], v[0:1], 2, v[72:73]
	s_waitcnt lgkmcnt(0)
	v_add_f32_e32 v98, v98, v99
	global_store_dword v[72:73], v98, off
.LBB0_919:
	s_or_b64 exec, exec, s[0:1]
	v_add_u32_e32 v72, 0x60, v68
	v_ashrrev_i32_e32 v73, 31, v72
	s_waitcnt lgkmcnt(0)
	v_lshlrev_b64 v[98:99], 11, v[72:73]
	v_lshl_add_u64 v[98:99], s[6:7], 0, v[98:99]
	v_lshl_add_u64 v[98:99], s[8:9], 1, v[98:99]
	v_lshl_add_u64 v[98:99], v[98:99], 0, v[70:71]
	v_add_u32_e32 v69, 0x4200, v69
	v_add_u32_e32 v102, v83, v69
	ds_read_b128 v[110:113], v102
	ds_read_b128 v[114:117], v102 offset:16
	s_waitcnt vmcnt(15)
	v_mov_b32_e32 v106, v168
	v_mov_b32_e32 v107, v169
	v_mov_b32_e32 v108, v170
	v_mov_b32_e32 v109, v171
	v_cvt_f32_f16_e32 v102, v106
	v_cvt_f32_f16_sdwa v103, v106 dst_sel:DWORD dst_unused:UNUSED_PAD src0_sel:WORD_1
	s_waitcnt lgkmcnt(1)
	v_pk_add_f32 v[102:103], v[110:111], v[102:103]
	s_nop 0
	v_cvt_pk_f16_f32 v106, v102, v103
	v_cvt_f32_f16_e32 v102, v107
	v_cvt_f32_f16_sdwa v103, v107 dst_sel:DWORD dst_unused:UNUSED_PAD src0_sel:WORD_1
	v_cvt_f32_f16_sdwa v71, v106 dst_sel:DWORD dst_unused:UNUSED_PAD src0_sel:WORD_1
	v_pk_add_f32 v[102:103], v[112:113], v[102:103]
	s_nop 0
	v_cvt_pk_f16_f32 v107, v102, v103
	v_cvt_f32_f16_e32 v102, v108
	v_cvt_f32_f16_sdwa v103, v108 dst_sel:DWORD dst_unused:UNUSED_PAD src0_sel:WORD_1
	v_mul_f32_e32 v71, v71, v71
	v_fma_mix_f32 v71, v106, v106, v71 op_sel_hi:[1,1,0]
	s_waitcnt lgkmcnt(0)
	v_pk_add_f32 v[102:103], v[114:115], v[102:103]
	s_nop 0
	v_cvt_pk_f16_f32 v108, v102, v103
	v_cvt_f32_f16_e32 v102, v109
	v_cvt_f32_f16_sdwa v103, v109 dst_sel:DWORD dst_unused:UNUSED_PAD src0_sel:WORD_1
	v_fma_mix_f32 v71, v107, v107, v71 op_sel_hi:[1,1,0]
	v_pk_add_f32 v[102:103], v[116:117], v[102:103]
	v_fma_mix_f32 v71, v107, v107, v71 op_sel:[1,1,0] op_sel_hi:[1,1,0]
	v_cvt_pk_f16_f32 v109, v102, v103
	v_fma_mix_f32 v71, v108, v108, v71 op_sel_hi:[1,1,0]
	global_store_dwordx4 v[98:99], v[106:109], off
	v_fma_mix_f32 v71, v108, v108, v71 op_sel:[1,1,0] op_sel_hi:[1,1,0]
	s_nop 0
	v_fma_mix_f32 v71, v109, v109, v71 op_sel_hi:[1,1,0]
	s_nop 0
	v_fma_mix_f32 v71, v109, v109, v71 op_sel:[1,1,0] op_sel_hi:[1,1,0]
	s_nop 1
	v_mov_b32_dpp v98, v71 quad_perm:[1,0,3,2] row_mask:0xf bank_mask:0xf
	s_waitcnt lgkmcnt(0)
	v_add_f32_e32 v71, v71, v98
	s_nop 1
	v_mov_b32_dpp v98, v71 quad_perm:[2,3,0,1] row_mask:0xf bank_mask:0xf
	s_waitcnt lgkmcnt(0)
	v_add_f32_e32 v71, v71, v98
	s_nop 1
	v_mov_b32_dpp v98, v71 row_half_mirror row_mask:0xf bank_mask:0xf
	s_and_saveexec_b64 s[0:1], vcc
	s_cbranch_execz .LBB0_921
	v_lshlrev_b64 v[72:73], 6, v[72:73]
	v_lshl_add_u64 v[72:73], s[2:3], 0, v[72:73]
	v_lshl_add_u64 v[72:73], v[0:1], 2, v[72:73]
	s_waitcnt lgkmcnt(0)
	v_add_f32_e32 v71, v71, v98
	global_store_dword v[72:73], v71, off
; DI float h_lo(unsigned u) { return (float)__builtin_bit_cast(h2_t, u)[0]; }
; DI float h_hi(unsigned u) { return (float)__builtin_bit_cast(h2_t, u)[1]; }
; template <int EPI>
; DI void gemm_epilogue(const Ep& e, int m0, int n0) {
;     ...
; #pragma unroll
;     for (int p = 0; p < 8; ++p) {
;       const int row = p * 32 + (t >> 4), c8 = (t & 15) * 8;
;       const float4 a = *(const float4*)(T + row * 132 + c8), b = *(const float4*)(T + row * 132 + c8 + 4);
;       bf16_t* bp = e.xb + (size_t)(m0 + row) * DM + n0 + c8;
;       const uint4 xo4 = *(const uint4*)bp;
;       uint4 u;
;       u.x = pack2h(h_lo(xo4.x) + a.x, h_hi(xo4.x) + a.y); u.y = pack2h(h_lo(xo4.y) + a.z, h_hi(xo4.y) + a.w);
;       u.z = pack2h(h_lo(xo4.z) + b.x, h_hi(xo4.z) + b.y); u.w = pack2h(h_lo(xo4.w) + b.z, h_hi(xo4.w) + b.w);
;       *(uint4*)bp = u;
;       const float r0 = h_lo(u.x), r1 = h_hi(u.x), r2 = h_lo(u.y), r3 = h_hi(u.y);
;       const float r4 = h_lo(u.z), r5 = h_hi(u.z), r6 = h_lo(u.w), r7 = h_hi(u.w);
;       float s2 = r0 * r0 + r1 * r1 + r2 * r2 + r3 * r3 + r4 * r4 + r5 * r5 + r6 * r6 + r7 * r7;
;       s2 += __shfl_xor(s2, 1); s2 += __shfl_xor(s2, 2); s2 += __shfl_xor(s2, 4);
;       if ((t & 7) == 0) e.ss_out[(size_t)(m0 + row) * 16 + ((n0 + c8) >> 6)] = s2;
.LBB0_921:
	s_or_b64 exec, exec, s[0:1]
	v_add_u32_e32 v72, 0x80, v68
	v_ashrrev_i32_e32 v73, 31, v72
	s_waitcnt lgkmcnt(0)
	v_lshlrev_b64 v[98:99], 11, v[72:73]
	v_lshl_add_u64 v[98:99], s[6:7], 0, v[98:99]
	v_lshl_add_u64 v[98:99], s[8:9], 1, v[98:99]
	v_mov_b32_e32 v71, v2
	v_lshl_add_u64 v[98:99], v[98:99], 0, v[70:71]
	v_add_u32_e32 v69, 0x4200, v69
	v_add_u32_e32 v83, v83, v69
	ds_read_b128 v[110:113], v83
	ds_read_b128 v[114:117], v83 offset:16
	s_waitcnt vmcnt(15)
	v_mov_b32_e32 v106, v172
	v_mov_b32_e32 v107, v173
	v_mov_b32_e32 v108, v174
	v_mov_b32_e32 v109, v175
	v_cvt_f32_f16_e32 v102, v106
	v_cvt_f32_f16_sdwa v103, v106 dst_sel:DWORD dst_unused:UNUSED_PAD src0_sel:WORD_1
	s_waitcnt lgkmcnt(1)
	v_pk_add_f32 v[102:103], v[110:111], v[102:103]
	s_nop 0
	v_cvt_pk_f16_f32 v106, v102, v103
	v_cvt_f32_f16_e32 v102, v107
	v_cvt_f32_f16_sdwa v103, v107 dst_sel:DWORD dst_unused:UNUSED_PAD src0_sel:WORD_1
	v_cvt_f32_f16_sdwa v69, v106 dst_sel:DWORD dst_unused:UNUSED_PAD src0_sel:WORD_1
	v_pk_add_f32 v[102:103], v[112:113], v[102:103]
	s_nop 0
	v_cvt_pk_f16_f32 v107, v102, v103
	v_cvt_f32_f16_e32 v102, v108
	v_cvt_f32_f16_sdwa v103, v108 dst_sel:DWORD dst_unused:UNUSED_PAD src0_sel:WORD_1
	v_mul_f32_e32 v69, v69, v69
	v_fma_mix_f32 v69, v106, v106, v69 op_sel_hi:[1,1,0]
	s_waitcnt lgkmcnt(0)
	v_pk_add_f32 v[102:103], v[114:115], v[102:103]
	s_nop 0
	v_cvt_pk_f16_f32 v108, v102, v103
	v_cvt_f32_f16_e32 v102, v109
	v_cvt_f32_f16_sdwa v103, v109 dst_sel:DWORD dst_unused:UNUSED_PAD src0_sel:WORD_1
	v_fma_mix_f32 v69, v107, v107, v69 op_sel_hi:[1,1,0]
	v_pk_add_f32 v[102:103], v[116:117], v[102:103]
	v_fma_mix_f32 v69, v107, v107, v69 op_sel:[1,1,0] op_sel_hi:[1,1,0]
	v_cvt_pk_f16_f32 v109, v102, v103
	v_fma_mix_f32 v69, v108, v108, v69 op_sel_hi:[1,1,0]
	global_store_dwordx4 v[98:99], v[106:109], off
	v_fma_mix_f32 v69, v108, v108, v69 op_sel:[1,1,0] op_sel_hi:[1,1,0]
	s_nop 0
	v_fma_mix_f32 v69, v109, v109, v69 op_sel_hi:[1,1,0]
	s_nop 0
	v_fma_mix_f32 v69, v109, v109, v69 op_sel:[1,1,0] op_sel_hi:[1,1,0]
	s_nop 1
	v_mov_b32_dpp v98, v69 quad_perm:[1,0,3,2] row_mask:0xf bank_mask:0xf
	s_waitcnt lgkmcnt(0)
	v_add_f32_e32 v69, v69, v98
	s_nop 1
	v_mov_b32_dpp v98, v69 quad_perm:[2,3,0,1] row_mask:0xf bank_mask:0xf
	s_waitcnt lgkmcnt(0)
	v_add_f32_e32 v69, v69, v98
	s_nop 1
	v_mov_b32_dpp v98, v69 row_half_mirror row_mask:0xf bank_mask:0xf
	s_and_saveexec_b64 s[0:1], vcc
	s_cbranch_execz .LBB0_923
	v_lshlrev_b64 v[72:73], 6, v[72:73]
	v_lshl_add_u64 v[72:73], s[2:3], 0, v[72:73]
	v_lshl_add_u64 v[72:73], v[0:1], 2, v[72:73]
	s_waitcnt lgkmcnt(0)
	v_add_f32_e32 v69, v69, v98
	global_store_dword v[72:73], v69, off
.LBB0_923:
	s_or_b64 exec, exec, s[0:1]
	v_add_u32_e32 v72, 0xa0, v68
	v_ashrrev_i32_e32 v73, 31, v72
	s_waitcnt lgkmcnt(0)
	v_lshlrev_b64 v[98:99], 11, v[72:73]
	v_lshl_add_u64 v[98:99], s[6:7], 0, v[98:99]
	v_lshl_add_u64 v[98:99], s[8:9], 1, v[98:99]
	v_lshl_add_u64 v[98:99], v[98:99], 0, v[70:71]
	ds_read_b128 v[110:113], v83 offset:16896
	ds_read_b128 v[114:117], v83 offset:16912
	s_waitcnt vmcnt(15)
	v_mov_b32_e32 v106, v176
	v_mov_b32_e32 v107, v177
	v_mov_b32_e32 v108, v178
	v_mov_b32_e32 v109, v179
	v_cvt_f32_f16_e32 v102, v106
	v_cvt_f32_f16_sdwa v103, v106 dst_sel:DWORD dst_unused:UNUSED_PAD src0_sel:WORD_1
	s_waitcnt lgkmcnt(1)
	v_pk_add_f32 v[102:103], v[110:111], v[102:103]
	s_nop 0
	v_cvt_pk_f16_f32 v106, v102, v103
	v_cvt_f32_f16_e32 v102, v107
	v_cvt_f32_f16_sdwa v103, v107 dst_sel:DWORD dst_unused:UNUSED_PAD src0_sel:WORD_1
	v_cvt_f32_f16_sdwa v69, v106 dst_sel:DWORD dst_unused:UNUSED_PAD src0_sel:WORD_1
	v_pk_add_f32 v[102:103], v[112:113], v[102:103]
	s_nop 0
	v_cvt_pk_f16_f32 v107, v102, v103
	v_cvt_f32_f16_e32 v102, v108
	v_cvt_f32_f16_sdwa v103, v108 dst_sel:DWORD dst_unused:UNUSED_PAD src0_sel:WORD_1
	v_mul_f32_e32 v69, v69, v69
	v_fma_mix_f32 v69, v106, v106, v69 op_sel_hi:[1,1,0]
	s_waitcnt lgkmcnt(0)
	v_pk_add_f32 v[102:103], v[114:115], v[102:103]
	s_nop 0
	v_cvt_pk_f16_f32 v108, v102, v103
	v_cvt_f32_f16_e32 v102, v109
	v_cvt_f32_f16_sdwa v103, v109 dst_sel:DWORD dst_unused:UNUSED_PAD src0_sel:WORD_1
	v_fma_mix_f32 v69, v107, v107, v69 op_sel_hi:[1,1,0]
	v_pk_add_f32 v[102:103], v[116:117], v[102:103]
	v_fma_mix_f32 v69, v107, v107, v69 op_sel:[1,1,0] op_sel_hi:[1,1,0]
	v_cvt_pk_f16_f32 v109, v102, v103
	v_fma_mix_f32 v69, v108, v108, v69 op_sel_hi:[1,1,0]
	global_store_dwordx4 v[98:99], v[106:109], off
	v_fma_mix_f32 v69, v108, v108, v69 op_sel:[1,1,0] op_sel_hi:[1,1,0]
	s_nop 0
	v_fma_mix_f32 v69, v109, v109, v69 op_sel_hi:[1,1,0]
	s_nop 0
	v_fma_mix_f32 v69, v109, v109, v69 op_sel:[1,1,0] op_sel_hi:[1,1,0]
	s_nop 1
	v_mov_b32_dpp v71, v69 quad_perm:[1,0,3,2] row_mask:0xf bank_mask:0xf
	s_waitcnt lgkmcnt(0)
	v_add_f32_e32 v69, v69, v71
	s_nop 1
	v_mov_b32_dpp v71, v69 quad_perm:[2,3,0,1] row_mask:0xf bank_mask:0xf
	s_waitcnt lgkmcnt(0)
	v_add_f32_e32 v69, v69, v71
	s_nop 1
	v_mov_b32_dpp v71, v69 row_half_mirror row_mask:0xf bank_mask:0xf
	s_and_saveexec_b64 s[0:1], vcc
	s_cbranch_execz .LBB0_925
	v_lshlrev_b64 v[72:73], 6, v[72:73]
	v_lshl_add_u64 v[72:73], s[2:3], 0, v[72:73]
	v_lshl_add_u64 v[72:73], v[0:1], 2, v[72:73]
	s_waitcnt lgkmcnt(0)
	v_add_f32_e32 v69, v69, v71
	global_store_dword v[72:73], v69, off
; DI float h_lo(unsigned u) { return (float)__builtin_bit_cast(h2_t, u)[0]; }
; DI float h_hi(unsigned u) { return (float)__builtin_bit_cast(h2_t, u)[1]; }
; template <int EPI>
; DI void gemm_epilogue(const Ep& e, int m0, int n0) {
;     ...
; #pragma unroll
;     for (int p = 0; p < 8; ++p) {
;       const int row = p * 32 + (t >> 4), c8 = (t & 15) * 8;
;       const float4 a = *(const float4*)(T + row * 132 + c8), b = *(const float4*)(T + row * 132 + c8 + 4);
;       bf16_t* bp = e.xb + (size_t)(m0 + row) * DM + n0 + c8;
;       const uint4 xo4 = *(const uint4*)bp;
;       uint4 u;
;       u.x = pack2h(h_lo(xo4.x) + a.x, h_hi(xo4.x) + a.y); u.y = pack2h(h_lo(xo4.y) + a.z, h_hi(xo4.y) + a.w);
;       u.z = pack2h(h_lo(xo4.z) + b.x, h_hi(xo4.z) + b.y); u.w = pack2h(h_lo(xo4.w) + b.z, h_hi(xo4.w) + b.w);
;       *(uint4*)bp = u;
;       const float r0 = h_lo(u.x), r1 = h_hi(u.x), r2 = h_lo(u.y), r3 = h_hi(u.y);
;       const float r4 = h_lo(u.z), r5 = h_hi(u.z), r6 = h_lo(u.w), r7 = h_hi(u.w);
;       float s2 = r0 * r0 + r1 * r1 + r2 * r2 + r3 * r3 + r4 * r4 + r5 * r5 + r6 * r6 + r7 * r7;
;       s2 += __shfl_xor(s2, 1); s2 += __shfl_xor(s2, 2); s2 += __shfl_xor(s2, 4);
;       if ((t & 7) == 0) e.ss_out[(size_t)(m0 + row) * 16 + ((n0 + c8) >> 6)] = s2;
.LBB0_925:
	s_or_b64 exec, exec, s[0:1]
	v_add_u32_e32 v72, 0xc0, v68
	v_ashrrev_i32_e32 v73, 31, v72
	v_lshlrev_b64 v[98:99], 11, v[72:73]
	v_lshl_add_u64 v[98:99], s[6:7], 0, v[98:99]
	v_lshl_add_u64 v[98:99], s[8:9], 1, v[98:99]
	s_waitcnt lgkmcnt(0)
	v_mov_b32_e32 v71, v2
	v_lshl_add_u64 v[98:99], v[98:99], 0, v[70:71]
	ds_read_b128 v[110:113], v83 offset:33792
	ds_read_b128 v[114:117], v83 offset:33808
	s_waitcnt vmcnt(15)
	v_mov_b32_e32 v106, v180
	v_mov_b32_e32 v107, v181
	v_mov_b32_e32 v108, v182
	v_mov_b32_e32 v109, v183
	v_cvt_f32_f16_e32 v102, v106
	v_cvt_f32_f16_sdwa v103, v106 dst_sel:DWORD dst_unused:UNUSED_PAD src0_sel:WORD_1
	s_waitcnt lgkmcnt(1)
	v_pk_add_f32 v[102:103], v[110:111], v[102:103]
	s_nop 0
	v_cvt_pk_f16_f32 v106, v102, v103
	v_cvt_f32_f16_e32 v102, v107
	v_cvt_f32_f16_sdwa v103, v107 dst_sel:DWORD dst_unused:UNUSED_PAD src0_sel:WORD_1
	v_cvt_f32_f16_sdwa v69, v106 dst_sel:DWORD dst_unused:UNUSED_PAD src0_sel:WORD_1
	v_pk_add_f32 v[102:103], v[112:113], v[102:103]
	s_nop 0
	v_cvt_pk_f16_f32 v107, v102, v103
	v_cvt_f32_f16_e32 v102, v108
	v_cvt_f32_f16_sdwa v103, v108 dst_sel:DWORD dst_unused:UNUSED_PAD src0_sel:WORD_1
	v_mul_f32_e32 v69, v69, v69
	v_fma_mix_f32 v69, v106, v106, v69 op_sel_hi:[1,1,0]
	s_waitcnt lgkmcnt(0)
	v_pk_add_f32 v[102:103], v[114:115], v[102:103]
	s_nop 0
	v_cvt_pk_f16_f32 v108, v102, v103
	v_cvt_f32_f16_e32 v102, v109
	v_cvt_f32_f16_sdwa v103, v109 dst_sel:DWORD dst_unused:UNUSED_PAD src0_sel:WORD_1
	v_fma_mix_f32 v69, v107, v107, v69 op_sel_hi:[1,1,0]
	v_pk_add_f32 v[102:103], v[116:117], v[102:103]
	v_fma_mix_f32 v69, v107, v107, v69 op_sel:[1,1,0] op_sel_hi:[1,1,0]
	v_cvt_pk_f16_f32 v109, v102, v103
	v_fma_mix_f32 v69, v108, v108, v69 op_sel_hi:[1,1,0]
	global_store_dwordx4 v[98:99], v[106:109], off
	v_fma_mix_f32 v69, v108, v108, v69 op_sel:[1,1,0] op_sel_hi:[1,1,0]
	s_nop 0
	v_fma_mix_f32 v69, v109, v109, v69 op_sel_hi:[1,1,0]
	s_nop 0
	v_fma_mix_f32 v69, v109, v109, v69 op_sel:[1,1,0] op_sel_hi:[1,1,0]
	s_nop 1
	v_mov_b32_dpp v98, v69 quad_perm:[1,0,3,2] row_mask:0xf bank_mask:0xf
	s_waitcnt lgkmcnt(0)
	v_add_f32_e32 v69, v69, v98
	s_nop 1
	v_mov_b32_dpp v98, v69 quad_perm:[2,3,0,1] row_mask:0xf bank_mask:0xf
	s_waitcnt lgkmcnt(0)
	v_add_f32_e32 v69, v69, v98
	s_nop 1
	v_mov_b32_dpp v98, v69 row_half_mirror row_mask:0xf bank_mask:0xf
	s_and_saveexec_b64 s[0:1], vcc
	s_cbranch_execz .LBB0_927
	v_lshlrev_b64 v[72:73], 6, v[72:73]
	v_lshl_add_u64 v[72:73], s[2:3], 0, v[72:73]
	v_lshl_add_u64 v[72:73], v[0:1], 2, v[72:73]
	s_waitcnt lgkmcnt(0)
	v_add_f32_e32 v69, v69, v98
	global_store_dword v[72:73], v69, off
.LBB0_927:
	s_or_b64 exec, exec, s[0:1]
	v_add_u32_e32 v68, 0xe0, v68
	v_ashrrev_i32_e32 v69, 31, v68
	v_lshlrev_b64 v[72:73], 11, v[68:69]
	v_lshl_add_u64 v[72:73], s[6:7], 0, v[72:73]
	v_lshl_add_u64 v[72:73], s[8:9], 1, v[72:73]
	s_waitcnt lgkmcnt(0)
	v_lshl_add_u64 v[98:99], v[72:73], 0, v[70:71]
	ds_read_b128 v[106:109], v83 offset:50688
	ds_read_b128 v[110:113], v83 offset:50704
	s_waitcnt vmcnt(15)
	v_mov_b32_e32 v70, v184
	v_mov_b32_e32 v71, v185
	v_mov_b32_e32 v72, v186
	v_mov_b32_e32 v73, v187
	v_cvt_f32_f16_e32 v102, v70
	v_cvt_f32_f16_sdwa v103, v70 dst_sel:DWORD dst_unused:UNUSED_PAD src0_sel:WORD_1
	s_waitcnt lgkmcnt(1)
	v_pk_add_f32 v[102:103], v[106:107], v[102:103]
	s_nop 0
	v_cvt_pk_f16_f32 v70, v102, v103
	v_cvt_f32_f16_e32 v102, v71
	v_cvt_f32_f16_sdwa v103, v71 dst_sel:DWORD dst_unused:UNUSED_PAD src0_sel:WORD_1
	v_cvt_f32_f16_sdwa v83, v70 dst_sel:DWORD dst_unused:UNUSED_PAD src0_sel:WORD_1
	v_pk_add_f32 v[102:103], v[108:109], v[102:103]
	s_nop 0
	v_cvt_pk_f16_f32 v71, v102, v103
	v_cvt_f32_f16_e32 v102, v72
	v_cvt_f32_f16_sdwa v103, v72 dst_sel:DWORD dst_unused:UNUSED_PAD src0_sel:WORD_1
	v_mul_f32_e32 v83, v83, v83
	s_waitcnt lgkmcnt(0)
	v_pk_add_f32 v[102:103], v[110:111], v[102:103]
	s_nop 0
	v_cvt_pk_f16_f32 v72, v102, v103
	v_cvt_f32_f16_e32 v102, v73
	v_cvt_f32_f16_sdwa v103, v73 dst_sel:DWORD dst_unused:UNUSED_PAD src0_sel:WORD_1
	v_pk_add_f32 v[102:103], v[112:113], v[102:103]
	s_nop 0
	v_cvt_pk_f16_f32 v73, v102, v103
	global_store_dwordx4 v[98:99], v[70:73], off
	s_nop 1
	v_fma_mix_f32 v70, v70, v70, v83 op_sel_hi:[1,1,0]
	s_nop 0
	v_fma_mix_f32 v70, v71, v71, v70 op_sel_hi:[1,1,0]
	s_nop 0
	v_fma_mix_f32 v70, v71, v71, v70 op_sel:[1,1,0] op_sel_hi:[1,1,0]
	s_nop 0
	v_fma_mix_f32 v70, v72, v72, v70 op_sel_hi:[1,1,0]
	s_nop 0
	v_fma_mix_f32 v70, v72, v72, v70 op_sel:[1,1,0] op_sel_hi:[1,1,0]
	s_nop 0
	v_fma_mix_f32 v70, v73, v73, v70 op_sel_hi:[1,1,0]
	s_nop 0
	v_fma_mix_f32 v70, v73, v73, v70 op_sel:[1,1,0] op_sel_hi:[1,1,0]
	s_nop 1
	v_mov_b32_dpp v71, v70 quad_perm:[1,0,3,2] row_mask:0xf bank_mask:0xf
	s_waitcnt lgkmcnt(0)
	v_add_f32_e32 v70, v70, v71
	s_nop 1
	v_mov_b32_dpp v71, v70 quad_perm:[2,3,0,1] row_mask:0xf bank_mask:0xf
	s_waitcnt lgkmcnt(0)
	v_add_f32_e32 v70, v70, v71
	s_nop 1
	v_mov_b32_dpp v71, v70 row_half_mirror row_mask:0xf bank_mask:0xf
	s_and_saveexec_b64 s[0:1], vcc
	s_cbranch_execz .LBB0_929
	v_lshlrev_b64 v[68:69], 6, v[68:69]
	v_lshl_add_u64 v[68:69], s[2:3], 0, v[68:69]
	v_lshl_add_u64 v[0:1], v[0:1], 2, v[68:69]
	s_waitcnt lgkmcnt(0)
	v_add_f32_e32 v68, v70, v71
	global_store_dword v[0:1], v68, off
; DI float h_lo(unsigned u) { return (float)__builtin_bit_cast(h2_t, u)[0]; }
; DI float h_hi(unsigned u) { return (float)__builtin_bit_cast(h2_t, u)[1]; }
; template <int EPI>
; DI void gemm_epilogue(const Ep& e, int m0, int n0) {
;     ...
;     for (int p = 0; p < 8; ++p) {
;       const int row = p * 32 + (t >> 4), c8 = (t & 15) * 8;
;       const float4 a = *(const float4*)(T + row * 132 + c8), b = *(const float4*)(T + row * 132 + c8 + 4);
;       bf16_t* bp = e.xb + (size_t)(m0 + row) * DM + n0 + c8;
;       const uint4 xo4 = *(const uint4*)bp;
;       uint4 u;
;       u.x = pack2h(h_lo(xo4.x) + a.x, h_hi(xo4.x) + a.y); u.y = pack2h(h_lo(xo4.y) + a.z, h_hi(xo4.y) + a.w);
;       u.z = pack2h(h_lo(xo4.z) + b.x, h_hi(xo4.z) + b.y); u.w = pack2h(h_lo(xo4.w) + b.z, h_hi(xo4.w) + b.w);
;       *(uint4*)bp = u;
;       const float r0 = h_lo(u.x), r1 = h_hi(u.x), r2 = h_lo(u.y), r3 = h_hi(u.y);
;       const float r4 = h_lo(u.z), r5 = h_hi(u.z), r6 = h_lo(u.w), r7 = h_hi(u.w);
;       float s2 = r0 * r0 + r1 * r1 + r2 * r2 + r3 * r3 + r4 * r4 + r5 * r5 + r6 * r6 + r7 * r7;
;       s2 += __shfl_xor(s2, 1); s2 += __shfl_xor(s2, 2); s2 += __shfl_xor(s2, 4);
;       if ((t & 7) == 0) e.ss_out[(size_t)(m0 + row) * 16 + ((n0 + c8) >> 6)] = s2;
;     ...
;   for (int bj = 0; bj < 2; ++bj) {
; #pragma unroll
;     for (int ai = 0; ai < 2; ++ai)
; #pragma unroll
;       for (int m = 0; m < 4; ++m)
; #pragma unroll
;         for (int n = 0; n < 2; ++n)
; #pragma unroll
;           for (int j = 0; j < 4; ++j)
;             T[(ai * 128 + wr * 64 + m * 16 + fq * 4 + j) * 132 + wc * 32 + n * 16 + fr] = acc[ai][bj][m][n][j];
;     __syncthreads();
;     gemm_epilogue<EPI>(e, m0, n0 + bj * 128);
.LBB0_929:
	s_or_b64 exec, exec, s[0:1]
	s_waitcnt lgkmcnt(0)
	s_barrier
	ds_write2_b32 v132, v4, v20 offset1:16
	ds_write2_b32 v132, v5, v21 offset0:132 offset1:148
	ds_write2_b32 v104, v6, v22 offset0:8 offset1:24
	ds_write2_b32 v104, v7, v23 offset0:140 offset1:156
	ds_write2_b32 v105, v8, v24 offset0:64 offset1:80
	ds_write2_b32 v105, v9, v25 offset0:196 offset1:212
	ds_write2_b32 v100, v10, v26 offset0:72 offset1:88
	ds_write2_b32 v100, v11, v27 offset0:204 offset1:220
	ds_write2_b32 v101, v12, v28 offset0:128 offset1:144
	ds_write2_b32 v92, v13, v29 offset0:4 offset1:20
	ds_write2_b32 v92, v14, v30 offset0:136 offset1:152
	ds_write2_b32 v93, v15, v31 offset0:12 offset1:28
	ds_write2_b32 v94, v16, v32 offset0:192 offset1:208
	ds_write2_b32 v84, v17, v33 offset0:68 offset1:84
	ds_write2_b32 v84, v18, v34 offset0:200 offset1:216
	ds_write2_b32 v85, v19, v35 offset0:76 offset1:92
	ds_write2_b32 v86, v36, v52 offset1:16
	ds_write2_b32 v87, v37, v53 offset1:16
	ds_write2_b32 v88, v38, v54 offset1:16
	ds_write2_b32 v89, v39, v55 offset1:16
	ds_write2_b32 v90, v40, v56 offset1:16
	ds_write2_b32 v91, v41, v57 offset1:16
	ds_write2_b32 v95, v42, v58 offset1:16
	ds_write2_b32 v96, v43, v59 offset1:16
	ds_write2_b32 v97, v44, v60 offset1:16
	ds_write2_b32 v80, v45, v61 offset1:16
	ds_write2_b32 v81, v46, v62 offset1:16
	ds_write2_b32 v82, v47, v63 offset1:16
	ds_write2_b32 v76, v48, v64 offset1:16
	ds_write2_b32 v77, v49, v65 offset1:16
	ds_write2_b32 v78, v50, v66 offset1:16
	ds_write2_b32 v79, v51, v67 offset1:16
	v_mov_b32_e32 v9, v224
	s_waitcnt lgkmcnt(0)
	s_barrier
	v_mov_b32_e32 v7, v2
	v_ashrrev_i32_e32 v8, 4, v9
	v_add_u32_e32 v4, s25, v8
	v_lshlrev_b32_e32 v0, 3, v9
	v_ashrrev_i32_e32 v5, 31, v4
	v_and_b32_e32 v30, 0x78, v0
	v_lshlrev_b64 v[0:1], 11, v[4:5]
	v_lshl_add_u64 v[0:1], s[6:7], 0, v[0:1]
	v_lshl_add_u64 v[0:1], s[8:9], 1, v[0:1]
	v_lshlrev_b32_e32 v6, 1, v30
	v_lshl_add_u64 v[24:25], v[0:1], 0, v[6:7]
	s_movk_i32 s0, 0x210
	v_mul_lo_u32 v8, v8, s0
	v_lshlrev_b32_e32 v10, 2, v30
	v_add_u32_e32 v0, v10, v8
	ds_read_b128 v[16:19], v0
	ds_read_b128 v[20:23], v0 offset:16
	v_and_b32_e32 v9, 7, v9
	v_cmp_eq_u32_e32 vcc, 0, v9
	s_waitcnt vmcnt(15)
	v_mov_b32_e32 v12, v188
	v_mov_b32_e32 v13, v189
	v_mov_b32_e32 v14, v190
	v_mov_b32_e32 v15, v191
	v_cvt_f32_f16_e32 v0, v12
	v_cvt_f32_f16_sdwa v1, v12 dst_sel:DWORD dst_unused:UNUSED_PAD src0_sel:WORD_1
	v_cvt_f32_f16_e32 v12, v13
	v_cvt_f32_f16_sdwa v13, v13 dst_sel:DWORD dst_unused:UNUSED_PAD src0_sel:WORD_1
	v_cvt_f32_f16_e32 v26, v14
	v_cvt_f32_f16_sdwa v27, v14 dst_sel:DWORD dst_unused:UNUSED_PAD src0_sel:WORD_1
	s_waitcnt lgkmcnt(1)
	v_pk_add_f32 v[0:1], v[16:17], v[0:1]
	v_cvt_f32_f16_e32 v28, v15
	v_cvt_f32_f16_sdwa v29, v15 dst_sel:DWORD dst_unused:UNUSED_PAD src0_sel:WORD_1
	v_pk_add_f32 v[14:15], v[18:19], v[12:13]
	v_cvt_pk_f16_f32 v12, v0, v1
	v_cvt_f32_f16_sdwa v11, v12 dst_sel:DWORD dst_unused:UNUSED_PAD src0_sel:WORD_1
	s_waitcnt lgkmcnt(0)
	v_pk_add_f32 v[0:1], v[20:21], v[26:27]
	v_cvt_pk_f16_f32 v13, v14, v15
	v_cvt_pk_f16_f32 v14, v0, v1
	v_pk_add_f32 v[0:1], v[22:23], v[28:29]
	s_nop 0
	v_cvt_pk_f16_f32 v15, v0, v1
	v_mul_f32_e32 v0, v11, v11
	v_fma_mix_f32 v0, v12, v12, v0 op_sel_hi:[1,1,0]
	global_store_dwordx4 v[24:25], v[12:15], off offset:256
	v_fma_mix_f32 v0, v13, v13, v0 op_sel_hi:[1,1,0]
	s_nop 0
	v_fma_mix_f32 v0, v13, v13, v0 op_sel:[1,1,0] op_sel_hi:[1,1,0]
	s_nop 0
	v_fma_mix_f32 v0, v14, v14, v0 op_sel_hi:[1,1,0]
	s_nop 0
	v_fma_mix_f32 v0, v14, v14, v0 op_sel:[1,1,0] op_sel_hi:[1,1,0]
	s_nop 0
	v_fma_mix_f32 v0, v15, v15, v0 op_sel_hi:[1,1,0]
	s_nop 0
	v_fma_mix_f32 v0, v15, v15, v0 op_sel:[1,1,0] op_sel_hi:[1,1,0]
	s_nop 1
	v_mov_b32_dpp v1, v0 quad_perm:[1,0,3,2] row_mask:0xf bank_mask:0xf
	s_waitcnt lgkmcnt(0)
	v_add_f32_e32 v0, v0, v1
	s_nop 1
	v_mov_b32_dpp v1, v0 quad_perm:[2,3,0,1] row_mask:0xf bank_mask:0xf
	s_waitcnt lgkmcnt(0)
	v_add_f32_e32 v9, v0, v1
	s_nop 1
	v_mov_b32_dpp v11, v9 row_half_mirror row_mask:0xf bank_mask:0xf
	v_or_b32_e32 v0, s30, v30
	v_ashrrev_i32_e32 v0, 6, v0
	v_ashrrev_i32_e32 v1, 31, v0
	s_and_saveexec_b64 s[0:1], vcc
	s_cbranch_execz .LBB0_931
	v_lshlrev_b64 v[12:13], 6, v[4:5]
	v_lshl_add_u64 v[12:13], s[2:3], 0, v[12:13]
	v_lshl_add_u64 v[12:13], v[0:1], 2, v[12:13]
	s_waitcnt lgkmcnt(0)
	v_add_f32_e32 v5, v9, v11
	global_store_dword v[12:13], v5, off
.LBB0_931:
	s_or_b64 exec, exec, s[0:1]
	v_add_u32_e32 v5, 0x4200, v8
	v_add_u32_e32 v8, 32, v4
	v_ashrrev_i32_e32 v9, 31, v8
	v_lshlrev_b64 v[12:13], 11, v[8:9]
	v_lshl_add_u64 v[12:13], s[6:7], 0, v[12:13]
	v_lshl_add_u64 v[12:13], s[8:9], 1, v[12:13]
	v_lshl_add_u64 v[24:25], v[12:13], 0, v[6:7]
	s_waitcnt lgkmcnt(0)
	v_add_u32_e32 v11, v10, v5
	ds_read_b128 v[16:19], v11
	ds_read_b128 v[20:23], v11 offset:16
	s_waitcnt vmcnt(15)
	v_mov_b32_e32 v12, v192
	v_mov_b32_e32 v13, v193
	v_mov_b32_e32 v14, v194
	v_mov_b32_e32 v15, v195
	v_cvt_f32_f16_e32 v26, v12
	v_cvt_f32_f16_sdwa v27, v12 dst_sel:DWORD dst_unused:UNUSED_PAD src0_sel:WORD_1
	s_waitcnt lgkmcnt(1)
	v_pk_add_f32 v[16:17], v[16:17], v[26:27]
	s_nop 0
	v_cvt_pk_f16_f32 v12, v16, v17
	v_cvt_f32_f16_e32 v16, v13
	v_cvt_f32_f16_sdwa v17, v13 dst_sel:DWORD dst_unused:UNUSED_PAD src0_sel:WORD_1
	v_cvt_f32_f16_sdwa v7, v12 dst_sel:DWORD dst_unused:UNUSED_PAD src0_sel:WORD_1
	v_pk_add_f32 v[16:17], v[18:19], v[16:17]
	s_nop 0
	v_cvt_pk_f16_f32 v13, v16, v17
	v_cvt_f32_f16_e32 v16, v14
	v_cvt_f32_f16_sdwa v17, v14 dst_sel:DWORD dst_unused:UNUSED_PAD src0_sel:WORD_1
	v_mul_f32_e32 v7, v7, v7
	v_fma_mix_f32 v7, v12, v12, v7 op_sel_hi:[1,1,0]
	s_waitcnt lgkmcnt(0)
	v_pk_add_f32 v[16:17], v[20:21], v[16:17]
	s_nop 0
	v_cvt_pk_f16_f32 v14, v16, v17
	v_cvt_f32_f16_e32 v16, v15
	v_cvt_f32_f16_sdwa v17, v15 dst_sel:DWORD dst_unused:UNUSED_PAD src0_sel:WORD_1
	v_fma_mix_f32 v7, v13, v13, v7 op_sel_hi:[1,1,0]
	v_pk_add_f32 v[16:17], v[22:23], v[16:17]
	v_fma_mix_f32 v7, v13, v13, v7 op_sel:[1,1,0] op_sel_hi:[1,1,0]
	v_cvt_pk_f16_f32 v15, v16, v17
	v_fma_mix_f32 v7, v14, v14, v7 op_sel_hi:[1,1,0]
	global_store_dwordx4 v[24:25], v[12:15], off offset:256
	v_fma_mix_f32 v7, v14, v14, v7 op_sel:[1,1,0] op_sel_hi:[1,1,0]
	s_nop 0
	v_fma_mix_f32 v7, v15, v15, v7 op_sel_hi:[1,1,0]
	s_nop 0
	v_fma_mix_f32 v7, v15, v15, v7 op_sel:[1,1,0] op_sel_hi:[1,1,0]
	s_nop 1
	v_mov_b32_dpp v11, v7 quad_perm:[1,0,3,2] row_mask:0xf bank_mask:0xf
	s_waitcnt lgkmcnt(0)
	v_add_f32_e32 v7, v7, v11
	s_nop 1
	v_mov_b32_dpp v11, v7 quad_perm:[2,3,0,1] row_mask:0xf bank_mask:0xf
	s_waitcnt lgkmcnt(0)
	v_add_f32_e32 v7, v7, v11
	s_nop 1
	v_mov_b32_dpp v11, v7 row_half_mirror row_mask:0xf bank_mask:0xf
	s_and_saveexec_b64 s[0:1], vcc
	s_cbranch_execz .LBB0_933
	v_lshlrev_b64 v[8:9], 6, v[8:9]
	v_lshl_add_u64 v[8:9], s[2:3], 0, v[8:9]
	v_lshl_add_u64 v[8:9], v[0:1], 2, v[8:9]
	s_waitcnt lgkmcnt(0)
	v_add_f32_e32 v7, v7, v11
	global_store_dword v[8:9], v7, off
; DI float h_lo(unsigned u) { return (float)__builtin_bit_cast(h2_t, u)[0]; }
; DI float h_hi(unsigned u) { return (float)__builtin_bit_cast(h2_t, u)[1]; }
; template <int EPI>
; DI void gemm_epilogue(const Ep& e, int m0, int n0) {
;     ...
;     for (int p = 0; p < 8; ++p) {
;       const int row = p * 32 + (t >> 4), c8 = (t & 15) * 8;
;       const float4 a = *(const float4*)(T + row * 132 + c8), b = *(const float4*)(T + row * 132 + c8 + 4);
;       bf16_t* bp = e.xb + (size_t)(m0 + row) * DM + n0 + c8;
;       const uint4 xo4 = *(const uint4*)bp;
;       uint4 u;
;       u.x = pack2h(h_lo(xo4.x) + a.x, h_hi(xo4.x) + a.y); u.y = pack2h(h_lo(xo4.y) + a.z, h_hi(xo4.y) + a.w);
;       u.z = pack2h(h_lo(xo4.z) + b.x, h_hi(xo4.z) + b.y); u.w = pack2h(h_lo(xo4.w) + b.z, h_hi(xo4.w) + b.w);
;       *(uint4*)bp = u;
;       const float r0 = h_lo(u.x), r1 = h_hi(u.x), r2 = h_lo(u.y), r3 = h_hi(u.y);
;       const float r4 = h_lo(u.z), r5 = h_hi(u.z), r6 = h_lo(u.w), r7 = h_hi(u.w);
;       float s2 = r0 * r0 + r1 * r1 + r2 * r2 + r3 * r3 + r4 * r4 + r5 * r5 + r6 * r6 + r7 * r7;
;       s2 += __shfl_xor(s2, 1); s2 += __shfl_xor(s2, 2); s2 += __shfl_xor(s2, 4);
;       if ((t & 7) == 0) e.ss_out[(size_t)(m0 + row) * 16 + ((n0 + c8) >> 6)] = s2;
.LBB0_933:
	s_or_b64 exec, exec, s[0:1]
	v_add_u32_e32 v8, 64, v4
	v_ashrrev_i32_e32 v9, 31, v8
	v_lshlrev_b64 v[12:13], 11, v[8:9]
	v_lshl_add_u64 v[12:13], s[6:7], 0, v[12:13]
	v_lshl_add_u64 v[12:13], s[8:9], 1, v[12:13]
	v_mov_b32_e32 v7, v2
	v_lshl_add_u64 v[24:25], v[12:13], 0, v[6:7]
	v_add_u32_e32 v5, 0x4200, v5
	s_waitcnt lgkmcnt(0)
	v_add_u32_e32 v11, v10, v5
	ds_read_b128 v[16:19], v11
	ds_read_b128 v[20:23], v11 offset:16
	s_waitcnt vmcnt(15)
	v_mov_b32_e32 v12, v196
	v_mov_b32_e32 v13, v197
	v_mov_b32_e32 v14, v198
	v_mov_b32_e32 v15, v199
	v_cvt_f32_f16_e32 v26, v12
	v_cvt_f32_f16_sdwa v27, v12 dst_sel:DWORD dst_unused:UNUSED_PAD src0_sel:WORD_1
	s_waitcnt lgkmcnt(1)
	v_pk_add_f32 v[16:17], v[16:17], v[26:27]
	s_nop 0
	v_cvt_pk_f16_f32 v12, v16, v17
	v_cvt_f32_f16_e32 v16, v13
	v_cvt_f32_f16_sdwa v17, v13 dst_sel:DWORD dst_unused:UNUSED_PAD src0_sel:WORD_1
	v_cvt_f32_f16_sdwa v11, v12 dst_sel:DWORD dst_unused:UNUSED_PAD src0_sel:WORD_1
	v_pk_add_f32 v[16:17], v[18:19], v[16:17]
	s_nop 0
	v_cvt_pk_f16_f32 v13, v16, v17
	v_cvt_f32_f16_e32 v16, v14
	v_cvt_f32_f16_sdwa v17, v14 dst_sel:DWORD dst_unused:UNUSED_PAD src0_sel:WORD_1
	v_mul_f32_e32 v11, v11, v11
	v_fma_mix_f32 v11, v12, v12, v11 op_sel_hi:[1,1,0]
	s_waitcnt lgkmcnt(0)
	v_pk_add_f32 v[16:17], v[20:21], v[16:17]
	s_nop 0
	v_cvt_pk_f16_f32 v14, v16, v17
	v_cvt_f32_f16_e32 v16, v15
	v_cvt_f32_f16_sdwa v17, v15 dst_sel:DWORD dst_unused:UNUSED_PAD src0_sel:WORD_1
	v_fma_mix_f32 v11, v13, v13, v11 op_sel_hi:[1,1,0]
	v_pk_add_f32 v[16:17], v[22:23], v[16:17]
	v_fma_mix_f32 v11, v13, v13, v11 op_sel:[1,1,0] op_sel_hi:[1,1,0]
	v_cvt_pk_f16_f32 v15, v16, v17
	v_fma_mix_f32 v11, v14, v14, v11 op_sel_hi:[1,1,0]
	global_store_dwordx4 v[24:25], v[12:15], off offset:256
	v_fma_mix_f32 v11, v14, v14, v11 op_sel:[1,1,0] op_sel_hi:[1,1,0]
	s_nop 0
	v_fma_mix_f32 v11, v15, v15, v11 op_sel_hi:[1,1,0]
	s_nop 0
	v_fma_mix_f32 v11, v15, v15, v11 op_sel:[1,1,0] op_sel_hi:[1,1,0]
	s_nop 1
	v_mov_b32_dpp v12, v11 quad_perm:[1,0,3,2] row_mask:0xf bank_mask:0xf
	s_waitcnt lgkmcnt(0)
	v_add_f32_e32 v11, v11, v12
	s_nop 1
	v_mov_b32_dpp v12, v11 quad_perm:[2,3,0,1] row_mask:0xf bank_mask:0xf
	s_waitcnt lgkmcnt(0)
	v_add_f32_e32 v11, v11, v12
	s_nop 1
	v_mov_b32_dpp v12, v11 row_half_mirror row_mask:0xf bank_mask:0xf
	s_and_saveexec_b64 s[0:1], vcc
	s_cbranch_execz .LBB0_935
	v_lshlrev_b64 v[8:9], 6, v[8:9]
	v_lshl_add_u64 v[8:9], s[2:3], 0, v[8:9]
	v_lshl_add_u64 v[8:9], v[0:1], 2, v[8:9]
	s_waitcnt lgkmcnt(0)
	v_add_f32_e32 v11, v11, v12
	global_store_dword v[8:9], v11, off
.LBB0_935:
	s_or_b64 exec, exec, s[0:1]
	v_add_u32_e32 v8, 0x60, v4
	v_ashrrev_i32_e32 v9, 31, v8
	s_waitcnt lgkmcnt(0)
	v_lshlrev_b64 v[12:13], 11, v[8:9]
	v_lshl_add_u64 v[12:13], s[6:7], 0, v[12:13]
	v_lshl_add_u64 v[12:13], s[8:9], 1, v[12:13]
	v_lshl_add_u64 v[24:25], v[12:13], 0, v[6:7]
	v_add_u32_e32 v5, 0x4200, v5
	v_add_u32_e32 v11, v10, v5
	ds_read_b128 v[16:19], v11
	ds_read_b128 v[20:23], v11 offset:16
	s_waitcnt vmcnt(15)
	v_mov_b32_e32 v12, v200
	v_mov_b32_e32 v13, v201
	v_mov_b32_e32 v14, v202
	v_mov_b32_e32 v15, v203
	v_cvt_f32_f16_e32 v26, v12
	v_cvt_f32_f16_sdwa v27, v12 dst_sel:DWORD dst_unused:UNUSED_PAD src0_sel:WORD_1
	s_waitcnt lgkmcnt(1)
	v_pk_add_f32 v[16:17], v[16:17], v[26:27]
	s_nop 0
	v_cvt_pk_f16_f32 v12, v16, v17
	v_cvt_f32_f16_e32 v16, v13
	v_cvt_f32_f16_sdwa v17, v13 dst_sel:DWORD dst_unused:UNUSED_PAD src0_sel:WORD_1
	v_cvt_f32_f16_sdwa v7, v12 dst_sel:DWORD dst_unused:UNUSED_PAD src0_sel:WORD_1
	v_pk_add_f32 v[16:17], v[18:19], v[16:17]
	s_nop 0
	v_cvt_pk_f16_f32 v13, v16, v17
	v_cvt_f32_f16_e32 v16, v14
	v_cvt_f32_f16_sdwa v17, v14 dst_sel:DWORD dst_unused:UNUSED_PAD src0_sel:WORD_1
	v_mul_f32_e32 v7, v7, v7
	v_fma_mix_f32 v7, v12, v12, v7 op_sel_hi:[1,1,0]
	s_waitcnt lgkmcnt(0)
	v_pk_add_f32 v[16:17], v[20:21], v[16:17]
	s_nop 0
	v_cvt_pk_f16_f32 v14, v16, v17
	v_cvt_f32_f16_e32 v16, v15
	v_cvt_f32_f16_sdwa v17, v15 dst_sel:DWORD dst_unused:UNUSED_PAD src0_sel:WORD_1
	v_fma_mix_f32 v7, v13, v13, v7 op_sel_hi:[1,1,0]
	v_pk_add_f32 v[16:17], v[22:23], v[16:17]
	v_fma_mix_f32 v7, v13, v13, v7 op_sel:[1,1,0] op_sel_hi:[1,1,0]
	v_cvt_pk_f16_f32 v15, v16, v17
	v_fma_mix_f32 v7, v14, v14, v7 op_sel_hi:[1,1,0]
	global_store_dwordx4 v[24:25], v[12:15], off offset:256
	v_fma_mix_f32 v7, v14, v14, v7 op_sel:[1,1,0] op_sel_hi:[1,1,0]
	s_nop 0
	v_fma_mix_f32 v7, v15, v15, v7 op_sel_hi:[1,1,0]
	s_nop 0
	v_fma_mix_f32 v7, v15, v15, v7 op_sel:[1,1,0] op_sel_hi:[1,1,0]
	s_nop 1
	v_mov_b32_dpp v11, v7 quad_perm:[1,0,3,2] row_mask:0xf bank_mask:0xf
	s_waitcnt lgkmcnt(0)
	v_add_f32_e32 v7, v7, v11
	s_nop 1
	v_mov_b32_dpp v11, v7 quad_perm:[2,3,0,1] row_mask:0xf bank_mask:0xf
	s_waitcnt lgkmcnt(0)
	v_add_f32_e32 v7, v7, v11
	s_nop 1
	v_mov_b32_dpp v11, v7 row_half_mirror row_mask:0xf bank_mask:0xf
	s_and_saveexec_b64 s[0:1], vcc
	s_cbranch_execz .LBB0_937
	v_lshlrev_b64 v[8:9], 6, v[8:9]
	v_lshl_add_u64 v[8:9], s[2:3], 0, v[8:9]
	v_lshl_add_u64 v[8:9], v[0:1], 2, v[8:9]
	s_waitcnt lgkmcnt(0)
	v_add_f32_e32 v7, v7, v11
	global_store_dword v[8:9], v7, off
; DI float h_lo(unsigned u) { return (float)__builtin_bit_cast(h2_t, u)[0]; }
; DI float h_hi(unsigned u) { return (float)__builtin_bit_cast(h2_t, u)[1]; }
; template <int EPI>
; DI void gemm_epilogue(const Ep& e, int m0, int n0) {
;     ...
;     for (int p = 0; p < 8; ++p) {
;       const int row = p * 32 + (t >> 4), c8 = (t & 15) * 8;
;       const float4 a = *(const float4*)(T + row * 132 + c8), b = *(const float4*)(T + row * 132 + c8 + 4);
;       bf16_t* bp = e.xb + (size_t)(m0 + row) * DM + n0 + c8;
;       const uint4 xo4 = *(const uint4*)bp;
;       uint4 u;
;       u.x = pack2h(h_lo(xo4.x) + a.x, h_hi(xo4.x) + a.y); u.y = pack2h(h_lo(xo4.y) + a.z, h_hi(xo4.y) + a.w);
;       u.z = pack2h(h_lo(xo4.z) + b.x, h_hi(xo4.z) + b.y); u.w = pack2h(h_lo(xo4.w) + b.z, h_hi(xo4.w) + b.w);
;       *(uint4*)bp = u;
;       const float r0 = h_lo(u.x), r1 = h_hi(u.x), r2 = h_lo(u.y), r3 = h_hi(u.y);
;       const float r4 = h_lo(u.z), r5 = h_hi(u.z), r6 = h_lo(u.w), r7 = h_hi(u.w);
;       float s2 = r0 * r0 + r1 * r1 + r2 * r2 + r3 * r3 + r4 * r4 + r5 * r5 + r6 * r6 + r7 * r7;
;       s2 += __shfl_xor(s2, 1); s2 += __shfl_xor(s2, 2); s2 += __shfl_xor(s2, 4);
;       if ((t & 7) == 0) e.ss_out[(size_t)(m0 + row) * 16 + ((n0 + c8) >> 6)] = s2;
.LBB0_937:
	s_or_b64 exec, exec, s[0:1]
	v_add_u32_e32 v8, 0x80, v4
	v_ashrrev_i32_e32 v9, 31, v8
	v_lshlrev_b64 v[12:13], 11, v[8:9]
	v_lshl_add_u64 v[12:13], s[6:7], 0, v[12:13]
	v_lshl_add_u64 v[12:13], s[8:9], 1, v[12:13]
	v_mov_b32_e32 v7, v2
	v_lshl_add_u64 v[24:25], v[12:13], 0, v[6:7]
	v_add_u32_e32 v5, 0x4200, v5
	v_add_u32_e32 v10, v10, v5
	ds_read_b128 v[16:19], v10
	ds_read_b128 v[20:23], v10 offset:16
	s_waitcnt vmcnt(15)
	v_mov_b32_e32 v12, v204
	v_mov_b32_e32 v13, v205
	v_mov_b32_e32 v14, v206
	v_mov_b32_e32 v15, v207
	v_cvt_f32_f16_e32 v26, v12
	v_cvt_f32_f16_sdwa v27, v12 dst_sel:DWORD dst_unused:UNUSED_PAD src0_sel:WORD_1
	s_waitcnt lgkmcnt(1)
	v_pk_add_f32 v[16:17], v[16:17], v[26:27]
	s_nop 0
	v_cvt_pk_f16_f32 v12, v16, v17
	v_cvt_f32_f16_e32 v16, v13
	v_cvt_f32_f16_sdwa v17, v13 dst_sel:DWORD dst_unused:UNUSED_PAD src0_sel:WORD_1
	v_cvt_f32_f16_sdwa v5, v12 dst_sel:DWORD dst_unused:UNUSED_PAD src0_sel:WORD_1
	v_pk_add_f32 v[16:17], v[18:19], v[16:17]
	s_nop 0
	v_cvt_pk_f16_f32 v13, v16, v17
	v_cvt_f32_f16_e32 v16, v14
	v_cvt_f32_f16_sdwa v17, v14 dst_sel:DWORD dst_unused:UNUSED_PAD src0_sel:WORD_1
	v_mul_f32_e32 v5, v5, v5
	v_fma_mix_f32 v5, v12, v12, v5 op_sel_hi:[1,1,0]
	s_waitcnt lgkmcnt(0)
	v_pk_add_f32 v[16:17], v[20:21], v[16:17]
	s_nop 0
	v_cvt_pk_f16_f32 v14, v16, v17
	v_cvt_f32_f16_e32 v16, v15
	v_cvt_f32_f16_sdwa v17, v15 dst_sel:DWORD dst_unused:UNUSED_PAD src0_sel:WORD_1
	v_fma_mix_f32 v5, v13, v13, v5 op_sel_hi:[1,1,0]
	v_pk_add_f32 v[16:17], v[22:23], v[16:17]
	v_fma_mix_f32 v5, v13, v13, v5 op_sel:[1,1,0] op_sel_hi:[1,1,0]
	v_cvt_pk_f16_f32 v15, v16, v17
	v_fma_mix_f32 v5, v14, v14, v5 op_sel_hi:[1,1,0]
	global_store_dwordx4 v[24:25], v[12:15], off offset:256
	v_fma_mix_f32 v5, v14, v14, v5 op_sel:[1,1,0] op_sel_hi:[1,1,0]
	s_nop 0
	v_fma_mix_f32 v5, v15, v15, v5 op_sel_hi:[1,1,0]
	s_nop 0
	v_fma_mix_f32 v5, v15, v15, v5 op_sel:[1,1,0] op_sel_hi:[1,1,0]
	s_nop 1
	v_mov_b32_dpp v11, v5 quad_perm:[1,0,3,2] row_mask:0xf bank_mask:0xf
	s_waitcnt lgkmcnt(0)
	v_add_f32_e32 v5, v5, v11
	s_nop 1
	v_mov_b32_dpp v11, v5 quad_perm:[2,3,0,1] row_mask:0xf bank_mask:0xf
	s_waitcnt lgkmcnt(0)
	v_add_f32_e32 v5, v5, v11
	s_nop 1
	v_mov_b32_dpp v11, v5 row_half_mirror row_mask:0xf bank_mask:0xf
	s_and_saveexec_b64 s[0:1], vcc
	s_cbranch_execz .LBB0_939
	v_lshlrev_b64 v[8:9], 6, v[8:9]
	v_lshl_add_u64 v[8:9], s[2:3], 0, v[8:9]
	v_lshl_add_u64 v[8:9], v[0:1], 2, v[8:9]
	s_waitcnt lgkmcnt(0)
	v_add_f32_e32 v5, v5, v11
	global_store_dword v[8:9], v5, off
.LBB0_939:
	s_or_b64 exec, exec, s[0:1]
	v_add_u32_e32 v8, 0xa0, v4
	v_ashrrev_i32_e32 v9, 31, v8
	v_lshlrev_b64 v[12:13], 11, v[8:9]
	v_lshl_add_u64 v[12:13], s[6:7], 0, v[12:13]
	v_lshl_add_u64 v[12:13], s[8:9], 1, v[12:13]
	v_lshl_add_u64 v[24:25], v[12:13], 0, v[6:7]
	ds_read_b128 v[16:19], v10 offset:16896
	ds_read_b128 v[20:23], v10 offset:16912
	s_waitcnt vmcnt(15)
	v_mov_b32_e32 v12, v208
	v_mov_b32_e32 v13, v209
	v_mov_b32_e32 v14, v210
	v_mov_b32_e32 v15, v211
	v_cvt_f32_f16_e32 v26, v12
	v_cvt_f32_f16_sdwa v27, v12 dst_sel:DWORD dst_unused:UNUSED_PAD src0_sel:WORD_1
	s_waitcnt lgkmcnt(1)
	v_pk_add_f32 v[16:17], v[16:17], v[26:27]
	s_nop 0
	v_cvt_pk_f16_f32 v12, v16, v17
	v_cvt_f32_f16_e32 v16, v13
	v_cvt_f32_f16_sdwa v17, v13 dst_sel:DWORD dst_unused:UNUSED_PAD src0_sel:WORD_1
	v_cvt_f32_f16_sdwa v5, v12 dst_sel:DWORD dst_unused:UNUSED_PAD src0_sel:WORD_1
	v_pk_add_f32 v[16:17], v[18:19], v[16:17]
	s_nop 0
	v_cvt_pk_f16_f32 v13, v16, v17
	v_cvt_f32_f16_e32 v16, v14
	v_cvt_f32_f16_sdwa v17, v14 dst_sel:DWORD dst_unused:UNUSED_PAD src0_sel:WORD_1
	v_mul_f32_e32 v5, v5, v5
	v_fma_mix_f32 v5, v12, v12, v5 op_sel_hi:[1,1,0]
	s_waitcnt lgkmcnt(0)
	v_pk_add_f32 v[16:17], v[20:21], v[16:17]
	s_nop 0
	v_cvt_pk_f16_f32 v14, v16, v17
	v_cvt_f32_f16_e32 v16, v15
	v_cvt_f32_f16_sdwa v17, v15 dst_sel:DWORD dst_unused:UNUSED_PAD src0_sel:WORD_1
	v_fma_mix_f32 v5, v13, v13, v5 op_sel_hi:[1,1,0]
	v_pk_add_f32 v[16:17], v[22:23], v[16:17]
	v_fma_mix_f32 v5, v13, v13, v5 op_sel:[1,1,0] op_sel_hi:[1,1,0]
	v_cvt_pk_f16_f32 v15, v16, v17
	v_fma_mix_f32 v5, v14, v14, v5 op_sel_hi:[1,1,0]
	global_store_dwordx4 v[24:25], v[12:15], off offset:256
	v_fma_mix_f32 v5, v14, v14, v5 op_sel:[1,1,0] op_sel_hi:[1,1,0]
	s_nop 0
	v_fma_mix_f32 v5, v15, v15, v5 op_sel_hi:[1,1,0]
	s_nop 0
	v_fma_mix_f32 v5, v15, v15, v5 op_sel:[1,1,0] op_sel_hi:[1,1,0]
	s_nop 1
	v_mov_b32_dpp v7, v5 quad_perm:[1,0,3,2] row_mask:0xf bank_mask:0xf
	s_waitcnt lgkmcnt(0)
	v_add_f32_e32 v5, v5, v7
	s_nop 1
	v_mov_b32_dpp v7, v5 quad_perm:[2,3,0,1] row_mask:0xf bank_mask:0xf
	s_waitcnt lgkmcnt(0)
	v_add_f32_e32 v5, v5, v7
	s_nop 1
	v_mov_b32_dpp v7, v5 row_half_mirror row_mask:0xf bank_mask:0xf
	s_and_saveexec_b64 s[0:1], vcc
	s_cbranch_execz .LBB0_941
	v_lshlrev_b64 v[8:9], 6, v[8:9]
	v_lshl_add_u64 v[8:9], s[2:3], 0, v[8:9]
	v_lshl_add_u64 v[8:9], v[0:1], 2, v[8:9]
	s_waitcnt lgkmcnt(0)
	v_add_f32_e32 v5, v5, v7
	global_store_dword v[8:9], v5, off
; DI float h_lo(unsigned u) { return (float)__builtin_bit_cast(h2_t, u)[0]; }
; DI float h_hi(unsigned u) { return (float)__builtin_bit_cast(h2_t, u)[1]; }
; template <int EPI>
; DI void gemm_epilogue(const Ep& e, int m0, int n0) {
;     ...
;     for (int p = 0; p < 8; ++p) {
;       const int row = p * 32 + (t >> 4), c8 = (t & 15) * 8;
;       const float4 a = *(const float4*)(T + row * 132 + c8), b = *(const float4*)(T + row * 132 + c8 + 4);
;       bf16_t* bp = e.xb + (size_t)(m0 + row) * DM + n0 + c8;
;       const uint4 xo4 = *(const uint4*)bp;
;       uint4 u;
;       u.x = pack2h(h_lo(xo4.x) + a.x, h_hi(xo4.x) + a.y); u.y = pack2h(h_lo(xo4.y) + a.z, h_hi(xo4.y) + a.w);
;       u.z = pack2h(h_lo(xo4.z) + b.x, h_hi(xo4.z) + b.y); u.w = pack2h(h_lo(xo4.w) + b.z, h_hi(xo4.w) + b.w);
;       *(uint4*)bp = u;
;       const float r0 = h_lo(u.x), r1 = h_hi(u.x), r2 = h_lo(u.y), r3 = h_hi(u.y);
;       const float r4 = h_lo(u.z), r5 = h_hi(u.z), r6 = h_lo(u.w), r7 = h_hi(u.w);
;       float s2 = r0 * r0 + r1 * r1 + r2 * r2 + r3 * r3 + r4 * r4 + r5 * r5 + r6 * r6 + r7 * r7;
;       s2 += __shfl_xor(s2, 1); s2 += __shfl_xor(s2, 2); s2 += __shfl_xor(s2, 4);
;       if ((t & 7) == 0) e.ss_out[(size_t)(m0 + row) * 16 + ((n0 + c8) >> 6)] = s2;
.LBB0_941:
	s_or_b64 exec, exec, s[0:1]
	v_add_u32_e32 v8, 0xc0, v4
	v_ashrrev_i32_e32 v9, 31, v8
	v_lshlrev_b64 v[12:13], 11, v[8:9]
	v_lshl_add_u64 v[12:13], s[6:7], 0, v[12:13]
	v_lshl_add_u64 v[12:13], s[8:9], 1, v[12:13]
	s_waitcnt lgkmcnt(0)
	v_mov_b32_e32 v7, v2
	v_lshl_add_u64 v[24:25], v[12:13], 0, v[6:7]
	ds_read_b128 v[16:19], v10 offset:33792
	ds_read_b128 v[20:23], v10 offset:33808
	s_waitcnt vmcnt(15)
	v_mov_b32_e32 v12, v212
	v_mov_b32_e32 v13, v213
	v_mov_b32_e32 v14, v214
	v_mov_b32_e32 v15, v215
	v_cvt_f32_f16_e32 v26, v12
	v_cvt_f32_f16_sdwa v27, v12 dst_sel:DWORD dst_unused:UNUSED_PAD src0_sel:WORD_1
	s_waitcnt lgkmcnt(1)
	v_pk_add_f32 v[16:17], v[16:17], v[26:27]
	s_nop 0
	v_cvt_pk_f16_f32 v12, v16, v17
	v_cvt_f32_f16_e32 v16, v13
	v_cvt_f32_f16_sdwa v17, v13 dst_sel:DWORD dst_unused:UNUSED_PAD src0_sel:WORD_1
	v_cvt_f32_f16_sdwa v5, v12 dst_sel:DWORD dst_unused:UNUSED_PAD src0_sel:WORD_1
	v_pk_add_f32 v[16:17], v[18:19], v[16:17]
	s_nop 0
	v_cvt_pk_f16_f32 v13, v16, v17
	v_cvt_f32_f16_e32 v16, v14
	v_cvt_f32_f16_sdwa v17, v14 dst_sel:DWORD dst_unused:UNUSED_PAD src0_sel:WORD_1
	v_mul_f32_e32 v5, v5, v5
	v_fma_mix_f32 v5, v12, v12, v5 op_sel_hi:[1,1,0]
	s_waitcnt lgkmcnt(0)
	v_pk_add_f32 v[16:17], v[20:21], v[16:17]
	s_nop 0
	v_cvt_pk_f16_f32 v14, v16, v17
	v_cvt_f32_f16_e32 v16, v15
	v_cvt_f32_f16_sdwa v17, v15 dst_sel:DWORD dst_unused:UNUSED_PAD src0_sel:WORD_1
	v_fma_mix_f32 v5, v13, v13, v5 op_sel_hi:[1,1,0]
	v_pk_add_f32 v[16:17], v[22:23], v[16:17]
	v_fma_mix_f32 v5, v13, v13, v5 op_sel:[1,1,0] op_sel_hi:[1,1,0]
	v_cvt_pk_f16_f32 v15, v16, v17
	v_fma_mix_f32 v5, v14, v14, v5 op_sel_hi:[1,1,0]
	global_store_dwordx4 v[24:25], v[12:15], off offset:256
	v_fma_mix_f32 v5, v14, v14, v5 op_sel:[1,1,0] op_sel_hi:[1,1,0]
	s_nop 0
	v_fma_mix_f32 v5, v15, v15, v5 op_sel_hi:[1,1,0]
	s_nop 0
	v_fma_mix_f32 v5, v15, v15, v5 op_sel:[1,1,0] op_sel_hi:[1,1,0]
	s_nop 1
	v_mov_b32_dpp v11, v5 quad_perm:[1,0,3,2] row_mask:0xf bank_mask:0xf
	s_waitcnt lgkmcnt(0)
	v_add_f32_e32 v5, v5, v11
	s_nop 1
	v_mov_b32_dpp v11, v5 quad_perm:[2,3,0,1] row_mask:0xf bank_mask:0xf
	s_waitcnt lgkmcnt(0)
	v_add_f32_e32 v5, v5, v11
	s_nop 1
	v_mov_b32_dpp v11, v5 row_half_mirror row_mask:0xf bank_mask:0xf
	s_and_saveexec_b64 s[0:1], vcc
	s_cbranch_execz .LBB0_943
	v_lshlrev_b64 v[8:9], 6, v[8:9]
	v_lshl_add_u64 v[8:9], s[2:3], 0, v[8:9]
	v_lshl_add_u64 v[8:9], v[0:1], 2, v[8:9]
	s_waitcnt lgkmcnt(0)
	v_add_f32_e32 v5, v5, v11
	global_store_dword v[8:9], v5, off
.LBB0_943:
	s_or_b64 exec, exec, s[0:1]
	v_add_u32_e32 v4, 0xe0, v4
	v_ashrrev_i32_e32 v5, 31, v4
	v_lshlrev_b64 v[8:9], 11, v[4:5]
	v_lshl_add_u64 v[8:9], s[6:7], 0, v[8:9]
	v_lshl_add_u64 v[8:9], s[8:9], 1, v[8:9]
	v_lshl_add_u64 v[20:21], v[8:9], 0, v[6:7]
	ds_read_b128 v[12:15], v10 offset:50688
	ds_read_b128 v[16:19], v10 offset:50704
	s_waitcnt vmcnt(15)
	v_mov_b32_e32 v6, v216
	v_mov_b32_e32 v7, v217
	v_mov_b32_e32 v8, v218
	v_mov_b32_e32 v9, v219
	v_cvt_f32_f16_e32 v10, v6
	s_waitcnt lgkmcnt(2)
	v_cvt_f32_f16_sdwa v11, v6 dst_sel:DWORD dst_unused:UNUSED_PAD src0_sel:WORD_1
	s_waitcnt lgkmcnt(1)
	v_pk_add_f32 v[10:11], v[12:13], v[10:11]
	s_nop 0
	v_cvt_pk_f16_f32 v6, v10, v11
	v_cvt_f32_f16_e32 v10, v7
	v_cvt_f32_f16_sdwa v11, v7 dst_sel:DWORD dst_unused:UNUSED_PAD src0_sel:WORD_1
	v_pk_add_f32 v[10:11], v[14:15], v[10:11]
	s_nop 0
	v_cvt_pk_f16_f32 v7, v10, v11
	v_cvt_f32_f16_e32 v10, v8
	v_cvt_f32_f16_sdwa v11, v8 dst_sel:DWORD dst_unused:UNUSED_PAD src0_sel:WORD_1
	s_waitcnt lgkmcnt(0)
	v_pk_add_f32 v[10:11], v[16:17], v[10:11]
	s_nop 0
	v_cvt_pk_f16_f32 v8, v10, v11
	v_cvt_f32_f16_e32 v10, v9
	v_cvt_f32_f16_sdwa v11, v9 dst_sel:DWORD dst_unused:UNUSED_PAD src0_sel:WORD_1
	v_pk_add_f32 v[10:11], v[18:19], v[10:11]
	s_nop 0
	v_cvt_pk_f16_f32 v9, v10, v11
	v_cvt_f32_f16_sdwa v10, v6 dst_sel:DWORD dst_unused:UNUSED_PAD src0_sel:WORD_1
	global_store_dwordx4 v[20:21], v[6:9], off offset:256
	v_mul_f32_e32 v10, v10, v10
	s_nop 0
	v_fma_mix_f32 v6, v6, v6, v10 op_sel_hi:[1,1,0]
	s_nop 0
	v_fma_mix_f32 v6, v7, v7, v6 op_sel_hi:[1,1,0]
	s_nop 0
	v_fma_mix_f32 v6, v7, v7, v6 op_sel:[1,1,0] op_sel_hi:[1,1,0]
	s_nop 0
	v_fma_mix_f32 v6, v8, v8, v6 op_sel_hi:[1,1,0]
	s_nop 0
	v_fma_mix_f32 v6, v8, v8, v6 op_sel:[1,1,0] op_sel_hi:[1,1,0]
	s_nop 0
	v_fma_mix_f32 v6, v9, v9, v6 op_sel_hi:[1,1,0]
	s_nop 0
	v_fma_mix_f32 v6, v9, v9, v6 op_sel:[1,1,0] op_sel_hi:[1,1,0]
	s_nop 1
	v_mov_b32_dpp v3, v6 quad_perm:[1,0,3,2] row_mask:0xf bank_mask:0xf
	s_waitcnt lgkmcnt(0)
	v_add_f32_e32 v3, v6, v3
	s_nop 1
	v_mov_b32_dpp v6, v3 quad_perm:[2,3,0,1] row_mask:0xf bank_mask:0xf
	s_waitcnt lgkmcnt(0)
	v_add_f32_e32 v3, v3, v6
	s_nop 1
	v_mov_b32_dpp v6, v3 row_half_mirror row_mask:0xf bank_mask:0xf
	s_and_saveexec_b64 s[0:1], vcc
	s_cbranch_execz .LBB0_904
	v_lshlrev_b64 v[4:5], 6, v[4:5]
	v_lshl_add_u64 v[4:5], s[2:3], 0, v[4:5]
	v_lshl_add_u64 v[0:1], v[0:1], 2, v[4:5]
	s_waitcnt lgkmcnt(0)
	v_add_f32_e32 v3, v3, v6
	global_store_dword v[0:1], v3, off
	s_branch .LBB0_904
